# removed 24 redundant post-barrier lgkmcnt(0) waits from the six GEMM K-loops (on top of v52)
# speedup vs baseline: 1.0043x; 1.0043x over previous
; #define PG8_STAGE(bufoff, gbase, voff) do { _Pragma("unroll") for (int _i = 0; _i < 2; ++_i) \
;         __builtin_amdgcn_global_load_lds((const unsigned*)((const char*)(gbase) + (voff)[_i]), (PG8_LAS unsigned*)(lds + (bufoff) + ldsw + _i * 8192), 16, 0, 0); } while (0)
; #define PG8_LDA(dst, b, h) do { _Pragma("unroll") for (int m = 0; m < 4; ++m) _Pragma("unroll") for (int k = 0; k < 2; ++k) dst[m][k] = *(const PG8_LAS bf16x8*)(lds + PG8_SA(b, h) + aoff + m * 2048 + k * 1024); } while (0)
; #define PG8_LDB(dst, b, h) do { _Pragma("unroll") for (int n = 0; n < 2; ++n) _Pragma("unroll") for (int k = 0; k < 2; ++k) dst[n][k] = *(const PG8_LAS bf16x8*)(lds + PG8_SB(b, h) + boff + n * 2048 + k * 1024); } while (0)
; #define PG8_MMA(ai, bj, At, Bt) do { __builtin_amdgcn_s_setprio(1); _Pragma("unroll") for (int m = 0; m < 4; ++m) _Pragma("unroll") for (int n = 0; n < 2; ++n) _Pragma("unroll") for (int k = 0; k < 2; ++k) \
;         acc[ai][bj][m][n] = __builtin_amdgcn_mfma_f32_16x16x32_bf16(Bt[n][k], At[m][k], acc[ai][bj][m][n], 0, 0, 0); __builtin_amdgcn_s_setprio(0); } while (0)
; #define PG8_WAIT_V(n) asm volatile("s_waitcnt vmcnt(" #n ")" ::: "memory")
; #define PG8_WAIT_L(n) asm volatile("s_waitcnt lgkmcnt(" #n ")" ::: "memory")
; #define PG8_BAR __builtin_amdgcn_s_barrier()
; #define PG8_SCHED __builtin_amdgcn_sched_barrier(0)
; template <class Epi, class Sched, bool ALIGN_EPI = false, bool SP2 = false>
; __device__ __forceinline__ void gemm_phase(PG8_LAS unsigned char* lds, const Gemm g, const Sched& S, const Epi& E) {
;     ...
;             const bool last = (t == nt_u - 2);
;             const char* a1 = cA + (size_t)(t + 1) * kstep;
;             const char* a2 = last ? nA : cA + (size_t)(t + 2) * kstep; const char* b2 = last ? nB : cB + (size_t)(t + 2) * kstep;
;             const char* a3 = a2 + kstep; const char* b3 = b2 + kstep;
;             if (last && has_next) S.a_ready(nxt);
;             if constexpr (SP2) {
;             PG8_LDB(B0, 0, 0); PG8_LDB(B1, 0, 1); PG8_SCHED; PG8_LDA(At, 0, 0); PG8_STAGE(PG8_SA(1, 1), a1 + hstep, voffA);
;             PG8_WAIT_V(8); PG8_WAIT_L(0); PG8_BAR; PG8_MMA(0, 0, At, B0); PG8_MMA(0, 1, At, B1); PG8_BAR; PG8_SCHED;
;             PG8_LDA(At, 0, 1); PG8_STAGE(PG8_SB(0, 0), b2, voffB); PG8_STAGE(PG8_SB(0, 1), b2 + hstep, voffB); PG8_STAGE(PG8_SA(0, 0), a2, voffA);
.LBB0_134:
	ds_read_b128 v[144:147], v152
	ds_read_b128 v[156:159], v152 offset:1024
	ds_read_b128 v[160:163], v152 offset:2048
	ds_read_b128 v[164:167], v152 offset:3072
	ds_read_b128 v[168:171], v153
	ds_read_b128 v[172:175], v153 offset:1024
	ds_read_b128 v[182:185], v153 offset:2048
	ds_read_b128 v[186:189], v153 offset:3072
	s_add_u32 s20, s62, 0xfffc0080
	s_addc_u32 s21, s63, -1
	s_cmp_eq_u32 s92, 12
	s_cselect_b32 s73, s12, s21
	s_cselect_b32 s72, s13, s20
	s_cselect_b32 s67, s29, s91
	s_cselect_b32 s66, s31, s90
	v_lshl_add_u64 v[224:225], s[62:63], 0, v[136:137]
	s_add_i32 m0, s51, 0xc000
	ds_read_b128 v[190:193], v154
	ds_read_b128 v[194:197], v154 offset:1024
	ds_read_b128 v[198:201], v154 offset:2048
	ds_read_b128 v[202:205], v154 offset:3072
	ds_read_b128 v[206:209], v154 offset:4096
	ds_read_b128 v[212:215], v154 offset:5120
	ds_read_b128 v[216:219], v154 offset:6144
	ds_read_b128 v[220:223], v154 offset:7168
	global_load_lds_dwordx4 v[224:225], off
	v_lshl_add_u64 v[224:225], s[62:63], 0, v[138:139]
	s_add_i32 m0, s51, 0xe000
	s_nop 0
	global_load_lds_dwordx4 v[224:225], off
	s_waitcnt vmcnt(8)
	s_waitcnt lgkmcnt(0)
	s_barrier
	v_mfma_f32_16x16x32_bf16 v[124:127], v[144:147], v[190:193], v[124:127]
	v_mfma_f32_16x16x32_bf16 v[120:123], v[160:163], v[190:193], v[120:123]
	v_mfma_f32_16x16x32_bf16 v[116:119], v[144:147], v[198:201], v[116:119]
	v_mfma_f32_16x16x32_bf16 v[108:111], v[160:163], v[198:201], v[108:111]
	v_mfma_f32_16x16x32_bf16 v[100:103], v[144:147], v[206:209], v[100:103]
	v_mfma_f32_16x16x32_bf16 v[92:95], v[160:163], v[206:209], v[92:95]
	v_mfma_f32_16x16x32_bf16 v[84:87], v[144:147], v[216:219], v[84:87]
	v_mfma_f32_16x16x32_bf16 v[76:79], v[160:163], v[216:219], v[76:79]
	v_mfma_f32_16x16x32_bf16 v[124:127], v[156:159], v[194:197], v[124:127]
	v_mfma_f32_16x16x32_bf16 v[120:123], v[164:167], v[194:197], v[120:123]
	v_mfma_f32_16x16x32_bf16 v[116:119], v[156:159], v[202:205], v[116:119]
	v_mfma_f32_16x16x32_bf16 v[108:111], v[164:167], v[202:205], v[108:111]
	v_mfma_f32_16x16x32_bf16 v[100:103], v[156:159], v[212:215], v[100:103]
	v_mfma_f32_16x16x32_bf16 v[92:95], v[164:167], v[212:215], v[92:95]
	v_mfma_f32_16x16x32_bf16 v[84:87], v[156:159], v[220:223], v[84:87]
	v_mfma_f32_16x16x32_bf16 v[76:79], v[164:167], v[220:223], v[76:79]
	v_mfma_f32_16x16x32_bf16 v[112:115], v[168:171], v[190:193], v[112:115]
	v_mfma_f32_16x16x32_bf16 v[104:107], v[182:185], v[190:193], v[104:107]
	v_mfma_f32_16x16x32_bf16 v[96:99], v[168:171], v[198:201], v[96:99]
	v_mfma_f32_16x16x32_bf16 v[88:91], v[182:185], v[198:201], v[88:91]
	v_mfma_f32_16x16x32_bf16 v[80:83], v[168:171], v[206:209], v[80:83]
	v_mfma_f32_16x16x32_bf16 v[72:75], v[182:185], v[206:209], v[72:75]
	v_mfma_f32_16x16x32_bf16 v[68:71], v[168:171], v[216:219], v[68:71]
	v_mfma_f32_16x16x32_bf16 v[64:67], v[182:185], v[216:219], v[64:67]
	v_mfma_f32_16x16x32_bf16 v[112:115], v[172:175], v[194:197], v[112:115]
	v_mfma_f32_16x16x32_bf16 v[104:107], v[186:189], v[194:197], v[104:107]
	v_mfma_f32_16x16x32_bf16 v[96:99], v[172:175], v[202:205], v[96:99]
	v_mfma_f32_16x16x32_bf16 v[88:91], v[186:189], v[202:205], v[88:91]
	v_mfma_f32_16x16x32_bf16 v[80:83], v[172:175], v[212:215], v[80:83]
	v_mfma_f32_16x16x32_bf16 v[72:75], v[186:189], v[212:215], v[72:75]
	v_mfma_f32_16x16x32_bf16 v[68:71], v[172:175], v[220:223], v[68:71]
	v_mfma_f32_16x16x32_bf16 v[64:67], v[186:189], v[220:223], v[64:67]
	s_barrier
	s_add_i32 s20, s81, s3
	v_lshl_add_u64 v[224:225], s[66:67], 0, v[132:133]
	s_mov_b32 m0, s20
	ds_read_b128 v[190:193], v154 offset:16384
	ds_read_b128 v[194:197], v154 offset:17408
	ds_read_b128 v[198:201], v154 offset:18432
	ds_read_b128 v[202:205], v154 offset:19456
	ds_read_b128 v[206:209], v154 offset:20480
	ds_read_b128 v[212:215], v154 offset:21504
	ds_read_b128 v[216:219], v154 offset:22528
	ds_read_b128 v[220:223], v154 offset:23552
	global_load_lds_dwordx4 v[224:225], off
	s_add_i32 m0, s20, 0x2000
	s_add_u32 s20, s66, 0x40000
	v_lshl_add_u64 v[226:227], s[66:67], 0, v[128:129]
	s_addc_u32 s21, s67, 0
	s_add_i32 s36, s82, s3
	global_load_lds_dwordx4 v[226:227], off
	v_lshl_add_u64 v[228:229], s[20:21], 0, v[132:133]
	s_mov_b32 m0, s36
	v_lshl_add_u64 v[230:231], s[72:73], 0, v[130:131]
	global_load_lds_dwordx4 v[228:229], off
	v_lshl_add_u64 v[228:229], s[20:21], 0, v[128:129]
	s_add_i32 m0, s36, 0x2000
	s_nop 0
	global_load_lds_dwordx4 v[228:229], off
	v_lshl_add_u64 v[228:229], s[72:73], 0, v[134:135]
	s_mov_b32 m0, s51
	s_nop 0
	global_load_lds_dwordx4 v[228:229], off
	s_mov_b32 m0, s75
	s_nop 0
	global_load_lds_dwordx4 v[230:231], off
	s_waitcnt vmcnt(8)
	s_waitcnt lgkmcnt(0)
	s_barrier
; #define PG8_STAGE(bufoff, gbase, voff) do { _Pragma("unroll") for (int _i = 0; _i < 2; ++_i) \
;         __builtin_amdgcn_global_load_lds((const unsigned*)((const char*)(gbase) + (voff)[_i]), (PG8_LAS unsigned*)(lds + (bufoff) + ldsw + _i * 8192), 16, 0, 0); } while (0)
; #define PG8_LDA(dst, b, h) do { _Pragma("unroll") for (int m = 0; m < 4; ++m) _Pragma("unroll") for (int k = 0; k < 2; ++k) dst[m][k] = *(const PG8_LAS bf16x8*)(lds + PG8_SA(b, h) + aoff + m * 2048 + k * 1024); } while (0)
; #define PG8_LDB(dst, b, h) do { _Pragma("unroll") for (int n = 0; n < 2; ++n) _Pragma("unroll") for (int k = 0; k < 2; ++k) dst[n][k] = *(const PG8_LAS bf16x8*)(lds + PG8_SB(b, h) + boff + n * 2048 + k * 1024); } while (0)
; #define PG8_MMA(ai, bj, At, Bt) do { __builtin_amdgcn_s_setprio(1); _Pragma("unroll") for (int m = 0; m < 4; ++m) _Pragma("unroll") for (int n = 0; n < 2; ++n) _Pragma("unroll") for (int k = 0; k < 2; ++k) \
;         acc[ai][bj][m][n] = __builtin_amdgcn_mfma_f32_16x16x32_bf16(Bt[n][k], At[m][k], acc[ai][bj][m][n], 0, 0, 0); __builtin_amdgcn_s_setprio(0); } while (0)
; #define PG8_WAIT_V(n) asm volatile("s_waitcnt vmcnt(" #n ")" ::: "memory")
; #define PG8_WAIT_L(n) asm volatile("s_waitcnt lgkmcnt(" #n ")" ::: "memory")
; #define PG8_BAR __builtin_amdgcn_s_barrier()
; #define PG8_SCHED __builtin_amdgcn_sched_barrier(0)
; template <class Epi, class Sched, bool ALIGN_EPI = false, bool SP2 = false>
; __device__ __forceinline__ void gemm_phase(PG8_LAS unsigned char* lds, const Gemm g, const Sched& S, const Epi& E) {
;     ...
;             PG8_WAIT_V(8); PG8_WAIT_L(0); PG8_BAR; PG8_MMA(0, 0, At, B0); PG8_MMA(0, 1, At, B1); PG8_BAR; PG8_SCHED;
;             PG8_LDA(At, 0, 1); PG8_STAGE(PG8_SB(0, 0), b2, voffB); PG8_STAGE(PG8_SB(0, 1), b2 + hstep, voffB); PG8_STAGE(PG8_SA(0, 0), a2, voffA);
;             PG8_WAIT_V(8); PG8_WAIT_L(0); PG8_BAR; PG8_MMA(1, 0, At, B0); PG8_MMA(1, 1, At, B1); PG8_BAR; PG8_SCHED;
;             PG8_LDB(B0, 1, 0); PG8_LDB(B1, 1, 1); PG8_SCHED; PG8_LDA(At, 1, 0); PG8_STAGE(PG8_SA(0, 1), a2 + hstep, voffA);
;             PG8_WAIT_V(8); PG8_WAIT_L(0); PG8_BAR; PG8_MMA(0, 0, At, B0); PG8_MMA(0, 1, At, B1); PG8_BAR; PG8_SCHED;
	v_mfma_f32_16x16x32_bf16 v[60:63], v[144:147], v[190:193], v[60:63]
	v_mfma_f32_16x16x32_bf16 v[56:59], v[160:163], v[190:193], v[56:59]
	v_mfma_f32_16x16x32_bf16 v[52:55], v[144:147], v[198:201], v[52:55]
	v_mfma_f32_16x16x32_bf16 v[44:47], v[160:163], v[198:201], v[44:47]
	v_mfma_f32_16x16x32_bf16 v[36:39], v[144:147], v[206:209], v[36:39]
	v_mfma_f32_16x16x32_bf16 v[28:31], v[160:163], v[206:209], v[28:31]
	v_mfma_f32_16x16x32_bf16 v[20:23], v[144:147], v[216:219], v[20:23]
	v_mfma_f32_16x16x32_bf16 v[12:15], v[160:163], v[216:219], v[12:15]
	v_mfma_f32_16x16x32_bf16 v[60:63], v[156:159], v[194:197], v[60:63]
	v_mfma_f32_16x16x32_bf16 v[56:59], v[164:167], v[194:197], v[56:59]
	v_mfma_f32_16x16x32_bf16 v[52:55], v[156:159], v[202:205], v[52:55]
	v_mfma_f32_16x16x32_bf16 v[44:47], v[164:167], v[202:205], v[44:47]
	v_mfma_f32_16x16x32_bf16 v[36:39], v[156:159], v[212:215], v[36:39]
	v_mfma_f32_16x16x32_bf16 v[28:31], v[164:167], v[212:215], v[28:31]
	v_mfma_f32_16x16x32_bf16 v[20:23], v[156:159], v[220:223], v[20:23]
	v_mfma_f32_16x16x32_bf16 v[12:15], v[164:167], v[220:223], v[12:15]
	v_mfma_f32_16x16x32_bf16 v[48:51], v[168:171], v[190:193], v[48:51]
	v_mfma_f32_16x16x32_bf16 v[40:43], v[182:185], v[190:193], v[40:43]
	v_mfma_f32_16x16x32_bf16 v[32:35], v[168:171], v[198:201], v[32:35]
	v_mfma_f32_16x16x32_bf16 v[24:27], v[182:185], v[198:201], v[24:27]
	v_mfma_f32_16x16x32_bf16 v[16:19], v[168:171], v[206:209], v[16:19]
	v_mfma_f32_16x16x32_bf16 v[8:11], v[182:185], v[206:209], v[8:11]
	v_mfma_f32_16x16x32_bf16 v[4:7], v[168:171], v[216:219], v[4:7]
	v_mfma_f32_16x16x32_bf16 v[0:3], v[182:185], v[216:219], v[0:3]
	v_mfma_f32_16x16x32_bf16 v[48:51], v[172:175], v[194:197], v[48:51]
	v_mfma_f32_16x16x32_bf16 v[40:43], v[186:189], v[194:197], v[40:43]
	v_mfma_f32_16x16x32_bf16 v[32:35], v[172:175], v[202:205], v[32:35]
	v_mfma_f32_16x16x32_bf16 v[24:27], v[186:189], v[202:205], v[24:27]
	v_mfma_f32_16x16x32_bf16 v[16:19], v[172:175], v[212:215], v[16:19]
	v_mfma_f32_16x16x32_bf16 v[8:11], v[186:189], v[212:215], v[8:11]
	v_mfma_f32_16x16x32_bf16 v[4:7], v[172:175], v[220:223], v[4:7]
	v_mfma_f32_16x16x32_bf16 v[0:3], v[186:189], v[220:223], v[0:3]
	s_barrier
	s_add_i32 s36, 0, 0x18000
	v_add_u32_e32 v155, s36, v150
	s_add_i32 s37, 0, 0x1c000
	ds_read_b128 v[144:147], v155
	ds_read_b128 v[156:159], v155 offset:1024
	ds_read_b128 v[160:163], v155 offset:2048
	ds_read_b128 v[164:167], v155 offset:3072
	v_add_u32_e32 v155, s37, v150
	ds_read_b128 v[168:171], v155
	ds_read_b128 v[172:175], v155 offset:1024
	ds_read_b128 v[182:185], v155 offset:2048
	ds_read_b128 v[186:189], v155 offset:3072
	s_add_u32 s20, s72, 0x40000
	s_addc_u32 s21, s73, 0
	s_mov_b32 m0, s76
	v_lshl_add_u64 v[232:233], s[20:21], 0, v[134:135]
	ds_read_b128 v[190:193], v154 offset:32768
	ds_read_b128 v[194:197], v154 offset:33792
	ds_read_b128 v[198:201], v154 offset:34816
	ds_read_b128 v[202:205], v154 offset:35840
	ds_read_b128 v[206:209], v154 offset:36864
	ds_read_b128 v[212:215], v154 offset:37888
	ds_read_b128 v[216:219], v154 offset:38912
	ds_read_b128 v[220:223], v154 offset:39936
	global_load_lds_dwordx4 v[232:233], off
	v_lshl_add_u64 v[232:233], s[20:21], 0, v[130:131]
	s_mov_b32 m0, s77
	s_nop 0
	global_load_lds_dwordx4 v[232:233], off
	s_waitcnt vmcnt(8)
	s_waitcnt lgkmcnt(0)
	s_barrier
	v_mfma_f32_16x16x32_bf16 v[124:127], v[144:147], v[190:193], v[124:127]
	v_mfma_f32_16x16x32_bf16 v[120:123], v[160:163], v[190:193], v[120:123]
	v_mfma_f32_16x16x32_bf16 v[116:119], v[144:147], v[198:201], v[116:119]
	v_mfma_f32_16x16x32_bf16 v[108:111], v[160:163], v[198:201], v[108:111]
	v_mfma_f32_16x16x32_bf16 v[100:103], v[144:147], v[206:209], v[100:103]
	v_mfma_f32_16x16x32_bf16 v[92:95], v[160:163], v[206:209], v[92:95]
	v_mfma_f32_16x16x32_bf16 v[84:87], v[144:147], v[216:219], v[84:87]
	v_mfma_f32_16x16x32_bf16 v[76:79], v[160:163], v[216:219], v[76:79]
	v_mfma_f32_16x16x32_bf16 v[124:127], v[156:159], v[194:197], v[124:127]
	v_mfma_f32_16x16x32_bf16 v[120:123], v[164:167], v[194:197], v[120:123]
	v_mfma_f32_16x16x32_bf16 v[116:119], v[156:159], v[202:205], v[116:119]
	v_mfma_f32_16x16x32_bf16 v[108:111], v[164:167], v[202:205], v[108:111]
	v_mfma_f32_16x16x32_bf16 v[100:103], v[156:159], v[212:215], v[100:103]
	v_mfma_f32_16x16x32_bf16 v[92:95], v[164:167], v[212:215], v[92:95]
	v_mfma_f32_16x16x32_bf16 v[84:87], v[156:159], v[220:223], v[84:87]
	v_mfma_f32_16x16x32_bf16 v[76:79], v[164:167], v[220:223], v[76:79]
	v_mfma_f32_16x16x32_bf16 v[112:115], v[168:171], v[190:193], v[112:115]
	v_mfma_f32_16x16x32_bf16 v[104:107], v[182:185], v[190:193], v[104:107]
	v_mfma_f32_16x16x32_bf16 v[96:99], v[168:171], v[198:201], v[96:99]
	v_mfma_f32_16x16x32_bf16 v[88:91], v[182:185], v[198:201], v[88:91]
	v_mfma_f32_16x16x32_bf16 v[80:83], v[168:171], v[206:209], v[80:83]
	v_mfma_f32_16x16x32_bf16 v[72:75], v[182:185], v[206:209], v[72:75]
	v_mfma_f32_16x16x32_bf16 v[68:71], v[168:171], v[216:219], v[68:71]
	v_mfma_f32_16x16x32_bf16 v[64:67], v[182:185], v[216:219], v[64:67]
	v_mfma_f32_16x16x32_bf16 v[112:115], v[172:175], v[194:197], v[112:115]
	v_mfma_f32_16x16x32_bf16 v[104:107], v[186:189], v[194:197], v[104:107]
	v_mfma_f32_16x16x32_bf16 v[96:99], v[172:175], v[202:205], v[96:99]
	v_mfma_f32_16x16x32_bf16 v[88:91], v[186:189], v[202:205], v[88:91]
	v_mfma_f32_16x16x32_bf16 v[80:83], v[172:175], v[212:215], v[80:83]
	v_mfma_f32_16x16x32_bf16 v[72:75], v[186:189], v[212:215], v[72:75]
	v_mfma_f32_16x16x32_bf16 v[68:71], v[172:175], v[220:223], v[68:71]
	v_mfma_f32_16x16x32_bf16 v[64:67], v[186:189], v[220:223], v[64:67]
	s_barrier
; #define PG8_STAGE(bufoff, gbase, voff) do { _Pragma("unroll") for (int _i = 0; _i < 2; ++_i) \
;         __builtin_amdgcn_global_load_lds((const unsigned*)((const char*)(gbase) + (voff)[_i]), (PG8_LAS unsigned*)(lds + (bufoff) + ldsw + _i * 8192), 16, 0, 0); } while (0)
; #define PG8_LDA(dst, b, h) do { _Pragma("unroll") for (int m = 0; m < 4; ++m) _Pragma("unroll") for (int k = 0; k < 2; ++k) dst[m][k] = *(const PG8_LAS bf16x8*)(lds + PG8_SA(b, h) + aoff + m * 2048 + k * 1024); } while (0)
; #define PG8_MMA(ai, bj, At, Bt) do { __builtin_amdgcn_s_setprio(1); _Pragma("unroll") for (int m = 0; m < 4; ++m) _Pragma("unroll") for (int n = 0; n < 2; ++n) _Pragma("unroll") for (int k = 0; k < 2; ++k) \
;         acc[ai][bj][m][n] = __builtin_amdgcn_mfma_f32_16x16x32_bf16(Bt[n][k], At[m][k], acc[ai][bj][m][n], 0, 0, 0); __builtin_amdgcn_s_setprio(0); } while (0)
; #define PG8_WAIT_V(n) asm volatile("s_waitcnt vmcnt(" #n ")" ::: "memory")
; #define PG8_WAIT_L(n) asm volatile("s_waitcnt lgkmcnt(" #n ")" ::: "memory")
; #define PG8_BAR __builtin_amdgcn_s_barrier()
; #define PG8_SCHED __builtin_amdgcn_sched_barrier(0)
; template <class Epi, class Sched, bool ALIGN_EPI = false, bool SP2 = false>
; __device__ __forceinline__ void gemm_phase(PG8_LAS unsigned char* lds, const Gemm g, const Sched& S, const Epi& E) {
;     ...
;         for (int t = 0; t < nt_u; t += 2) {
;             const bool last = (t == nt_u - 2);
;     ...
;             PG8_WAIT_V(8); PG8_WAIT_L(0); PG8_BAR; PG8_MMA(0, 0, At, B0); PG8_MMA(0, 1, At, B1); PG8_BAR; PG8_SCHED;
;             PG8_LDA(At, 1, 1); PG8_STAGE(PG8_SB(1, 0), b3, voffB); PG8_STAGE(PG8_SB(1, 1), b3 + hstep, voffB); PG8_STAGE(PG8_SA(1, 0), a3, voffA);
;             PG8_WAIT_V(8); PG8_WAIT_L(0); PG8_BAR; PG8_MMA(1, 0, At, B0); PG8_MMA(1, 1, At, B1); PG8_BAR; PG8_SCHED;
	s_add_i32 s20, s36, s3
	v_lshl_add_u64 v[224:225], v[224:225], 0, s[14:15]
	s_mov_b32 m0, s20
	ds_read_b128 v[190:193], v154 offset:49152
	ds_read_b128 v[194:197], v154 offset:50176
	ds_read_b128 v[198:201], v154 offset:51200
	ds_read_b128 v[202:205], v154 offset:52224
	ds_read_b128 v[206:209], v154 offset:53248
	ds_read_b128 v[212:215], v154 offset:54272
	ds_read_b128 v[216:219], v154 offset:55296
	ds_read_b128 v[220:223], v154 offset:56320
	global_load_lds_dwordx4 v[224:225], off
	s_add_i32 m0, s20, 0x2000
	s_add_u32 s20, s66, 0x40080
	v_lshl_add_u64 v[224:225], v[226:227], 0, s[14:15]
	s_addc_u32 s21, s67, 0
	s_add_i32 s36, s37, s3
	global_load_lds_dwordx4 v[224:225], off
	v_lshl_add_u64 v[224:225], s[20:21], 0, v[132:133]
	s_mov_b32 m0, s36
	s_nop 0
	global_load_lds_dwordx4 v[224:225], off
	v_lshl_add_u64 v[224:225], s[20:21], 0, v[128:129]
	s_add_i32 m0, s36, 0x2000
	s_nop 0
	global_load_lds_dwordx4 v[224:225], off
	v_lshl_add_u64 v[224:225], v[228:229], 0, s[14:15]
	s_mov_b32 m0, s10
	s_nop 0
	global_load_lds_dwordx4 v[224:225], off
	v_lshl_add_u64 v[224:225], v[230:231], 0, s[14:15]
	s_mov_b32 m0, s11
	s_nop 0
	global_load_lds_dwordx4 v[224:225], off
	s_waitcnt vmcnt(8)
	s_waitcnt lgkmcnt(0)
	s_barrier
	v_mfma_f32_16x16x32_bf16 v[60:63], v[144:147], v[190:193], v[60:63]
	v_mfma_f32_16x16x32_bf16 v[56:59], v[160:163], v[190:193], v[56:59]
	v_mfma_f32_16x16x32_bf16 v[52:55], v[144:147], v[198:201], v[52:55]
	v_mfma_f32_16x16x32_bf16 v[44:47], v[160:163], v[198:201], v[44:47]
	v_mfma_f32_16x16x32_bf16 v[36:39], v[144:147], v[206:209], v[36:39]
	v_mfma_f32_16x16x32_bf16 v[28:31], v[160:163], v[206:209], v[28:31]
	v_mfma_f32_16x16x32_bf16 v[20:23], v[144:147], v[216:219], v[20:23]
	v_mfma_f32_16x16x32_bf16 v[12:15], v[160:163], v[216:219], v[12:15]
	v_mfma_f32_16x16x32_bf16 v[60:63], v[156:159], v[194:197], v[60:63]
	v_mfma_f32_16x16x32_bf16 v[56:59], v[164:167], v[194:197], v[56:59]
	v_mfma_f32_16x16x32_bf16 v[52:55], v[156:159], v[202:205], v[52:55]
	v_mfma_f32_16x16x32_bf16 v[44:47], v[164:167], v[202:205], v[44:47]
	v_mfma_f32_16x16x32_bf16 v[36:39], v[156:159], v[212:215], v[36:39]
	v_mfma_f32_16x16x32_bf16 v[28:31], v[164:167], v[212:215], v[28:31]
	v_mfma_f32_16x16x32_bf16 v[20:23], v[156:159], v[220:223], v[20:23]
	v_mfma_f32_16x16x32_bf16 v[12:15], v[164:167], v[220:223], v[12:15]
	v_mfma_f32_16x16x32_bf16 v[48:51], v[168:171], v[190:193], v[48:51]
	v_mfma_f32_16x16x32_bf16 v[40:43], v[182:185], v[190:193], v[40:43]
	v_mfma_f32_16x16x32_bf16 v[32:35], v[168:171], v[198:201], v[32:35]
	v_mfma_f32_16x16x32_bf16 v[24:27], v[182:185], v[198:201], v[24:27]
	v_mfma_f32_16x16x32_bf16 v[16:19], v[168:171], v[206:209], v[16:19]
	v_mfma_f32_16x16x32_bf16 v[8:11], v[182:185], v[206:209], v[8:11]
	v_mfma_f32_16x16x32_bf16 v[4:7], v[168:171], v[216:219], v[4:7]
	v_mfma_f32_16x16x32_bf16 v[0:3], v[182:185], v[216:219], v[0:3]
	v_mfma_f32_16x16x32_bf16 v[48:51], v[172:175], v[194:197], v[48:51]
	v_mfma_f32_16x16x32_bf16 v[40:43], v[186:189], v[194:197], v[40:43]
	v_mfma_f32_16x16x32_bf16 v[32:35], v[172:175], v[202:205], v[32:35]
	v_mfma_f32_16x16x32_bf16 v[24:27], v[186:189], v[202:205], v[24:27]
	v_mfma_f32_16x16x32_bf16 v[16:19], v[172:175], v[212:215], v[16:19]
	v_mfma_f32_16x16x32_bf16 v[8:11], v[186:189], v[212:215], v[8:11]
	v_mfma_f32_16x16x32_bf16 v[4:7], v[172:175], v[220:223], v[4:7]
	v_mfma_f32_16x16x32_bf16 v[0:3], v[186:189], v[220:223], v[0:3]
	s_barrier
	s_add_i32 s92, s92, 2
	s_add_u32 s62, s62, 0x100
	s_addc_u32 s63, s63, 0
	s_add_u32 s90, s90, 0x100
	s_addc_u32 s91, s91, 0
	s_cmp_gt_u32 s92, 13
	s_cbranch_scc0 .LBB0_134
	s_and_b64 vcc, exec, s[26:27]
	s_cbranch_vccz .LBB0_137
	s_barrier

; #define PG8_STAGE(bufoff, gbase, voff) do { _Pragma("unroll") for (int _i = 0; _i < 2; ++_i) \
;         __builtin_amdgcn_global_load_lds((const unsigned*)((const char*)(gbase) + (voff)[_i]), (PG8_LAS unsigned*)(lds + (bufoff) + ldsw + _i * 8192), 16, 0, 0); } while (0)
; #define PG8_LDA(dst, b, h) do { _Pragma("unroll") for (int m = 0; m < 4; ++m) _Pragma("unroll") for (int k = 0; k < 2; ++k) dst[m][k] = *(const PG8_LAS bf16x8*)(lds + PG8_SA(b, h) + aoff + m * 2048 + k * 1024); } while (0)
; #define PG8_LDB(dst, b, h) do { _Pragma("unroll") for (int n = 0; n < 2; ++n) _Pragma("unroll") for (int k = 0; k < 2; ++k) dst[n][k] = *(const PG8_LAS bf16x8*)(lds + PG8_SB(b, h) + boff + n * 2048 + k * 1024); } while (0)
; #define PG8_MMA(ai, bj, At, Bt) do { __builtin_amdgcn_s_setprio(1); _Pragma("unroll") for (int m = 0; m < 4; ++m) _Pragma("unroll") for (int n = 0; n < 2; ++n) _Pragma("unroll") for (int k = 0; k < 2; ++k) \
;         acc[ai][bj][m][n] = __builtin_amdgcn_mfma_f32_16x16x32_bf16(Bt[n][k], At[m][k], acc[ai][bj][m][n], 0, 0, 0); __builtin_amdgcn_s_setprio(0); } while (0)
; #define PG8_WAIT_V(n) asm volatile("s_waitcnt vmcnt(" #n ")" ::: "memory")
; #define PG8_WAIT_L(n) asm volatile("s_waitcnt lgkmcnt(" #n ")" ::: "memory")
; #define PG8_BAR __builtin_amdgcn_s_barrier()
; #define PG8_SCHED __builtin_amdgcn_sched_barrier(0)
; template <class Epi, class Sched, bool ALIGN_EPI = false, bool SP2 = false>
; __device__ __forceinline__ void gemm_phase(PG8_LAS unsigned char* lds, const Gemm g, const Sched& S, const Epi& E) {
;     ...
;             const bool last = (t == nt_u - 2);
;             const char* a1 = cA + (size_t)(t + 1) * kstep;
;             const char* a2 = last ? nA : cA + (size_t)(t + 2) * kstep; const char* b2 = last ? nB : cB + (size_t)(t + 2) * kstep;
;             const char* a3 = a2 + kstep; const char* b3 = b2 + kstep;
;             if (last && has_next) S.a_ready(nxt);
;             if constexpr (SP2) {
;             PG8_LDB(B0, 0, 0); PG8_LDB(B1, 0, 1); PG8_SCHED; PG8_LDA(At, 0, 0); PG8_STAGE(PG8_SA(1, 1), a1 + hstep, voffA);
;             PG8_WAIT_V(8); PG8_WAIT_L(0); PG8_BAR; PG8_MMA(0, 0, At, B0); PG8_MMA(0, 1, At, B1); PG8_BAR; PG8_SCHED;
;             PG8_LDA(At, 0, 1); PG8_STAGE(PG8_SB(0, 0), b2, voffB); PG8_STAGE(PG8_SB(0, 1), b2 + hstep, voffB); PG8_STAGE(PG8_SA(0, 0), a2, voffA);
.LBB0_312:
	ds_read_b128 v[144:147], v151
	ds_read_b128 v[154:157], v151 offset:1024
	ds_read_b128 v[158:161], v151 offset:2048
	ds_read_b128 v[162:165], v151 offset:3072
	ds_read_b128 v[166:169], v152
	ds_read_b128 v[170:173], v152 offset:1024
	ds_read_b128 v[184:187], v152 offset:2048
	ds_read_b128 v[188:191], v152 offset:3072
	s_add_u32 s44, s42, 0x100
	s_addc_u32 s45, s43, 0
	s_cmp_eq_u32 s83, 2
	s_cselect_b32 s51, s1, s45
	s_cselect_b32 s50, s0, s44
	s_cselect_b32 s47, s41, s13
	s_cselect_b32 s46, s40, s12
	v_lshl_add_u64 v[174:175], s[42:43], 0, v[136:137]
	s_add_i32 m0, s63, 0xc000
	ds_read_b128 v[192:195], v153
	ds_read_b128 v[196:199], v153 offset:1024
	ds_read_b128 v[200:203], v153 offset:2048
	ds_read_b128 v[204:207], v153 offset:3072
	ds_read_b128 v[212:215], v153 offset:4096
	ds_read_b128 v[216:219], v153 offset:5120
	ds_read_b128 v[220:223], v153 offset:6144
	ds_read_b128 v[224:227], v153 offset:7168
	global_load_lds_dwordx4 v[174:175], off
	v_lshl_add_u64 v[174:175], s[42:43], 0, v[138:139]
	s_add_i32 m0, s63, 0xe000
	s_nop 0
	global_load_lds_dwordx4 v[174:175], off
	s_waitcnt vmcnt(8)
	s_waitcnt lgkmcnt(0)
	s_barrier
	v_mfma_f32_16x16x32_bf16 v[124:127], v[144:147], v[192:195], v[124:127]
	v_mfma_f32_16x16x32_bf16 v[120:123], v[158:161], v[192:195], v[120:123]
	v_mfma_f32_16x16x32_bf16 v[116:119], v[144:147], v[200:203], v[116:119]
	v_mfma_f32_16x16x32_bf16 v[108:111], v[158:161], v[200:203], v[108:111]
	v_mfma_f32_16x16x32_bf16 v[100:103], v[144:147], v[212:215], v[100:103]
	v_mfma_f32_16x16x32_bf16 v[92:95], v[158:161], v[212:215], v[92:95]
	v_mfma_f32_16x16x32_bf16 v[84:87], v[144:147], v[220:223], v[84:87]
	v_mfma_f32_16x16x32_bf16 v[76:79], v[158:161], v[220:223], v[76:79]
	v_mfma_f32_16x16x32_bf16 v[124:127], v[154:157], v[196:199], v[124:127]
	v_mfma_f32_16x16x32_bf16 v[120:123], v[162:165], v[196:199], v[120:123]
	v_mfma_f32_16x16x32_bf16 v[116:119], v[154:157], v[204:207], v[116:119]
	v_mfma_f32_16x16x32_bf16 v[108:111], v[162:165], v[204:207], v[108:111]
	v_mfma_f32_16x16x32_bf16 v[100:103], v[154:157], v[216:219], v[100:103]
	v_mfma_f32_16x16x32_bf16 v[92:95], v[162:165], v[216:219], v[92:95]
	v_mfma_f32_16x16x32_bf16 v[84:87], v[154:157], v[224:227], v[84:87]
	v_mfma_f32_16x16x32_bf16 v[76:79], v[162:165], v[224:227], v[76:79]
	v_mfma_f32_16x16x32_bf16 v[112:115], v[166:169], v[192:195], v[112:115]
	v_mfma_f32_16x16x32_bf16 v[104:107], v[184:187], v[192:195], v[104:107]
	v_mfma_f32_16x16x32_bf16 v[96:99], v[166:169], v[200:203], v[96:99]
	v_mfma_f32_16x16x32_bf16 v[88:91], v[184:187], v[200:203], v[88:91]
	v_mfma_f32_16x16x32_bf16 v[80:83], v[166:169], v[212:215], v[80:83]
	v_mfma_f32_16x16x32_bf16 v[72:75], v[184:187], v[212:215], v[72:75]
	v_mfma_f32_16x16x32_bf16 v[68:71], v[166:169], v[220:223], v[68:71]
	v_mfma_f32_16x16x32_bf16 v[64:67], v[184:187], v[220:223], v[64:67]
	v_mfma_f32_16x16x32_bf16 v[112:115], v[170:173], v[196:199], v[112:115]
	v_mfma_f32_16x16x32_bf16 v[104:107], v[188:191], v[196:199], v[104:107]
	v_mfma_f32_16x16x32_bf16 v[96:99], v[170:173], v[204:207], v[96:99]
	v_mfma_f32_16x16x32_bf16 v[88:91], v[188:191], v[204:207], v[88:91]
	v_mfma_f32_16x16x32_bf16 v[80:83], v[170:173], v[216:219], v[80:83]
	v_mfma_f32_16x16x32_bf16 v[72:75], v[188:191], v[216:219], v[72:75]
	v_mfma_f32_16x16x32_bf16 v[68:71], v[170:173], v[224:227], v[68:71]
	v_mfma_f32_16x16x32_bf16 v[64:67], v[188:191], v[224:227], v[64:67]
	s_barrier
	s_add_i32 s20, s76, s3
	v_lshl_add_u64 v[174:175], s[46:47], 0, v[132:133]
	s_mov_b32 m0, s20
	ds_read_b128 v[192:195], v153 offset:16384
	ds_read_b128 v[196:199], v153 offset:17408
	ds_read_b128 v[200:203], v153 offset:18432
	ds_read_b128 v[204:207], v153 offset:19456
	ds_read_b128 v[212:215], v153 offset:20480
	ds_read_b128 v[216:219], v153 offset:21504
	ds_read_b128 v[220:223], v153 offset:22528
	ds_read_b128 v[224:227], v153 offset:23552
	global_load_lds_dwordx4 v[174:175], off
	s_add_i32 m0, s20, 0x2000
	s_add_u32 s20, s46, 0x18000
	v_lshl_add_u64 v[208:209], s[46:47], 0, v[128:129]
	s_addc_u32 s21, s47, 0
	s_add_i32 s42, s77, s3
	global_load_lds_dwordx4 v[208:209], off
	v_lshl_add_u64 v[228:229], s[20:21], 0, v[132:133]
	s_mov_b32 m0, s42
	v_lshl_add_u64 v[230:231], s[50:51], 0, v[130:131]
	global_load_lds_dwordx4 v[228:229], off
	v_lshl_add_u64 v[228:229], s[20:21], 0, v[128:129]
	s_add_i32 m0, s42, 0x2000
	s_nop 0
	global_load_lds_dwordx4 v[228:229], off
	v_lshl_add_u64 v[228:229], s[50:51], 0, v[134:135]
	s_mov_b32 m0, s63
	s_nop 0
	global_load_lds_dwordx4 v[228:229], off
	s_mov_b32 m0, s66
	s_nop 0
	global_load_lds_dwordx4 v[230:231], off
	s_waitcnt vmcnt(8)
	s_waitcnt lgkmcnt(0)
	s_barrier
; #define PG8_STAGE(bufoff, gbase, voff) do { _Pragma("unroll") for (int _i = 0; _i < 2; ++_i) \
;         __builtin_amdgcn_global_load_lds((const unsigned*)((const char*)(gbase) + (voff)[_i]), (PG8_LAS unsigned*)(lds + (bufoff) + ldsw + _i * 8192), 16, 0, 0); } while (0)
; #define PG8_LDA(dst, b, h) do { _Pragma("unroll") for (int m = 0; m < 4; ++m) _Pragma("unroll") for (int k = 0; k < 2; ++k) dst[m][k] = *(const PG8_LAS bf16x8*)(lds + PG8_SA(b, h) + aoff + m * 2048 + k * 1024); } while (0)
; #define PG8_LDB(dst, b, h) do { _Pragma("unroll") for (int n = 0; n < 2; ++n) _Pragma("unroll") for (int k = 0; k < 2; ++k) dst[n][k] = *(const PG8_LAS bf16x8*)(lds + PG8_SB(b, h) + boff + n * 2048 + k * 1024); } while (0)
; #define PG8_MMA(ai, bj, At, Bt) do { __builtin_amdgcn_s_setprio(1); _Pragma("unroll") for (int m = 0; m < 4; ++m) _Pragma("unroll") for (int n = 0; n < 2; ++n) _Pragma("unroll") for (int k = 0; k < 2; ++k) \
;         acc[ai][bj][m][n] = __builtin_amdgcn_mfma_f32_16x16x32_bf16(Bt[n][k], At[m][k], acc[ai][bj][m][n], 0, 0, 0); __builtin_amdgcn_s_setprio(0); } while (0)
; #define PG8_WAIT_V(n) asm volatile("s_waitcnt vmcnt(" #n ")" ::: "memory")
; #define PG8_WAIT_L(n) asm volatile("s_waitcnt lgkmcnt(" #n ")" ::: "memory")
; #define PG8_BAR __builtin_amdgcn_s_barrier()
; #define PG8_SCHED __builtin_amdgcn_sched_barrier(0)
; template <class Epi, class Sched, bool ALIGN_EPI = false, bool SP2 = false>
; __device__ __forceinline__ void gemm_phase(PG8_LAS unsigned char* lds, const Gemm g, const Sched& S, const Epi& E) {
;     ...
;             PG8_WAIT_V(8); PG8_WAIT_L(0); PG8_BAR; PG8_MMA(0, 0, At, B0); PG8_MMA(0, 1, At, B1); PG8_BAR; PG8_SCHED;
;             PG8_LDA(At, 0, 1); PG8_STAGE(PG8_SB(0, 0), b2, voffB); PG8_STAGE(PG8_SB(0, 1), b2 + hstep, voffB); PG8_STAGE(PG8_SA(0, 0), a2, voffA);
;             PG8_WAIT_V(8); PG8_WAIT_L(0); PG8_BAR; PG8_MMA(1, 0, At, B0); PG8_MMA(1, 1, At, B1); PG8_BAR; PG8_SCHED;
;             PG8_LDB(B0, 1, 0); PG8_LDB(B1, 1, 1); PG8_SCHED; PG8_LDA(At, 1, 0); PG8_STAGE(PG8_SA(0, 1), a2 + hstep, voffA);
;             PG8_WAIT_V(8); PG8_WAIT_L(0); PG8_BAR; PG8_MMA(0, 0, At, B0); PG8_MMA(0, 1, At, B1); PG8_BAR; PG8_SCHED;
	v_mfma_f32_16x16x32_bf16 v[60:63], v[144:147], v[192:195], v[60:63]
	v_mfma_f32_16x16x32_bf16 v[56:59], v[158:161], v[192:195], v[56:59]
	v_mfma_f32_16x16x32_bf16 v[52:55], v[144:147], v[200:203], v[52:55]
	v_mfma_f32_16x16x32_bf16 v[44:47], v[158:161], v[200:203], v[44:47]
	v_mfma_f32_16x16x32_bf16 v[36:39], v[144:147], v[212:215], v[36:39]
	v_mfma_f32_16x16x32_bf16 v[28:31], v[158:161], v[212:215], v[28:31]
	v_mfma_f32_16x16x32_bf16 v[20:23], v[144:147], v[220:223], v[20:23]
	v_mfma_f32_16x16x32_bf16 v[12:15], v[158:161], v[220:223], v[12:15]
	v_mfma_f32_16x16x32_bf16 v[60:63], v[154:157], v[196:199], v[60:63]
	v_mfma_f32_16x16x32_bf16 v[56:59], v[162:165], v[196:199], v[56:59]
	v_mfma_f32_16x16x32_bf16 v[52:55], v[154:157], v[204:207], v[52:55]
	v_mfma_f32_16x16x32_bf16 v[44:47], v[162:165], v[204:207], v[44:47]
	v_mfma_f32_16x16x32_bf16 v[36:39], v[154:157], v[216:219], v[36:39]
	v_mfma_f32_16x16x32_bf16 v[28:31], v[162:165], v[216:219], v[28:31]
	v_mfma_f32_16x16x32_bf16 v[20:23], v[154:157], v[224:227], v[20:23]
	v_mfma_f32_16x16x32_bf16 v[12:15], v[162:165], v[224:227], v[12:15]
	v_mfma_f32_16x16x32_bf16 v[48:51], v[166:169], v[192:195], v[48:51]
	v_mfma_f32_16x16x32_bf16 v[40:43], v[184:187], v[192:195], v[40:43]
	v_mfma_f32_16x16x32_bf16 v[32:35], v[166:169], v[200:203], v[32:35]
	v_mfma_f32_16x16x32_bf16 v[24:27], v[184:187], v[200:203], v[24:27]
	v_mfma_f32_16x16x32_bf16 v[16:19], v[166:169], v[212:215], v[16:19]
	v_mfma_f32_16x16x32_bf16 v[8:11], v[184:187], v[212:215], v[8:11]
	v_mfma_f32_16x16x32_bf16 v[4:7], v[166:169], v[220:223], v[4:7]
	v_mfma_f32_16x16x32_bf16 v[0:3], v[184:187], v[220:223], v[0:3]
	v_mfma_f32_16x16x32_bf16 v[48:51], v[170:173], v[196:199], v[48:51]
	v_mfma_f32_16x16x32_bf16 v[40:43], v[188:191], v[196:199], v[40:43]
	v_mfma_f32_16x16x32_bf16 v[32:35], v[170:173], v[204:207], v[32:35]
	v_mfma_f32_16x16x32_bf16 v[24:27], v[188:191], v[204:207], v[24:27]
	v_mfma_f32_16x16x32_bf16 v[16:19], v[170:173], v[216:219], v[16:19]
	v_mfma_f32_16x16x32_bf16 v[8:11], v[188:191], v[216:219], v[8:11]
	v_mfma_f32_16x16x32_bf16 v[4:7], v[170:173], v[224:227], v[4:7]
	v_mfma_f32_16x16x32_bf16 v[0:3], v[188:191], v[224:227], v[0:3]
	s_barrier
	s_add_i32 s42, 0, 0x18000
	s_add_i32 s43, 0, 0x1c000
	v_add_u32_e32 v162, s42, v149
	v_add_u32_e32 v177, s43, v149
	ds_read_b128 v[144:147], v162
	ds_read_b128 v[154:157], v162 offset:1024
	ds_read_b128 v[158:161], v162 offset:2048
	ds_read_b128 v[162:165], v162 offset:3072
	ds_read_b128 v[166:169], v177
	ds_read_b128 v[170:173], v177 offset:1024
	ds_read_b128 v[184:187], v177 offset:2048
	ds_read_b128 v[188:191], v177 offset:3072
	s_add_u32 s20, s50, 0x18000
	s_addc_u32 s21, s51, 0
	s_mov_b32 m0, s67
	v_lshl_add_u64 v[232:233], s[20:21], 0, v[134:135]
	ds_read_b128 v[192:195], v153 offset:32768
	ds_read_b128 v[196:199], v153 offset:33792
	ds_read_b128 v[200:203], v153 offset:34816
	ds_read_b128 v[204:207], v153 offset:35840
	ds_read_b128 v[212:215], v153 offset:36864
	ds_read_b128 v[216:219], v153 offset:37888
	ds_read_b128 v[220:223], v153 offset:38912
	ds_read_b128 v[224:227], v153 offset:39936
	global_load_lds_dwordx4 v[232:233], off
	v_lshl_add_u64 v[232:233], s[20:21], 0, v[130:131]
	s_mov_b32 m0, s72
	s_nop 0
	global_load_lds_dwordx4 v[232:233], off
	s_waitcnt vmcnt(8)
	s_waitcnt lgkmcnt(0)
	s_barrier
	v_mfma_f32_16x16x32_bf16 v[124:127], v[144:147], v[192:195], v[124:127]
	v_mfma_f32_16x16x32_bf16 v[120:123], v[158:161], v[192:195], v[120:123]
	v_mfma_f32_16x16x32_bf16 v[116:119], v[144:147], v[200:203], v[116:119]
	v_mfma_f32_16x16x32_bf16 v[108:111], v[158:161], v[200:203], v[108:111]
	v_mfma_f32_16x16x32_bf16 v[100:103], v[144:147], v[212:215], v[100:103]
	v_mfma_f32_16x16x32_bf16 v[92:95], v[158:161], v[212:215], v[92:95]
	v_mfma_f32_16x16x32_bf16 v[84:87], v[144:147], v[220:223], v[84:87]
	v_mfma_f32_16x16x32_bf16 v[76:79], v[158:161], v[220:223], v[76:79]
	v_mfma_f32_16x16x32_bf16 v[124:127], v[154:157], v[196:199], v[124:127]
	v_mfma_f32_16x16x32_bf16 v[120:123], v[162:165], v[196:199], v[120:123]
	v_mfma_f32_16x16x32_bf16 v[116:119], v[154:157], v[204:207], v[116:119]
	v_mfma_f32_16x16x32_bf16 v[108:111], v[162:165], v[204:207], v[108:111]
	v_mfma_f32_16x16x32_bf16 v[100:103], v[154:157], v[216:219], v[100:103]
	v_mfma_f32_16x16x32_bf16 v[92:95], v[162:165], v[216:219], v[92:95]
	v_mfma_f32_16x16x32_bf16 v[84:87], v[154:157], v[224:227], v[84:87]
	v_mfma_f32_16x16x32_bf16 v[76:79], v[162:165], v[224:227], v[76:79]
	v_mfma_f32_16x16x32_bf16 v[112:115], v[166:169], v[192:195], v[112:115]
	v_mfma_f32_16x16x32_bf16 v[104:107], v[184:187], v[192:195], v[104:107]
	v_mfma_f32_16x16x32_bf16 v[96:99], v[166:169], v[200:203], v[96:99]
	v_mfma_f32_16x16x32_bf16 v[88:91], v[184:187], v[200:203], v[88:91]
	v_mfma_f32_16x16x32_bf16 v[80:83], v[166:169], v[212:215], v[80:83]
	v_mfma_f32_16x16x32_bf16 v[72:75], v[184:187], v[212:215], v[72:75]
	v_mfma_f32_16x16x32_bf16 v[68:71], v[166:169], v[220:223], v[68:71]
	v_mfma_f32_16x16x32_bf16 v[64:67], v[184:187], v[220:223], v[64:67]
	v_mfma_f32_16x16x32_bf16 v[112:115], v[170:173], v[196:199], v[112:115]
	v_mfma_f32_16x16x32_bf16 v[104:107], v[188:191], v[196:199], v[104:107]
	v_mfma_f32_16x16x32_bf16 v[96:99], v[170:173], v[204:207], v[96:99]
	v_mfma_f32_16x16x32_bf16 v[88:91], v[188:191], v[204:207], v[88:91]
	v_mfma_f32_16x16x32_bf16 v[80:83], v[170:173], v[216:219], v[80:83]
	v_mfma_f32_16x16x32_bf16 v[72:75], v[188:191], v[216:219], v[72:75]
	v_mfma_f32_16x16x32_bf16 v[68:71], v[170:173], v[224:227], v[68:71]
	v_mfma_f32_16x16x32_bf16 v[64:67], v[188:191], v[224:227], v[64:67]
	s_barrier
; #define PG8_STAGE(bufoff, gbase, voff) do { _Pragma("unroll") for (int _i = 0; _i < 2; ++_i) \
;         __builtin_amdgcn_global_load_lds((const unsigned*)((const char*)(gbase) + (voff)[_i]), (PG8_LAS unsigned*)(lds + (bufoff) + ldsw + _i * 8192), 16, 0, 0); } while (0)
; #define PG8_LDA(dst, b, h) do { _Pragma("unroll") for (int m = 0; m < 4; ++m) _Pragma("unroll") for (int k = 0; k < 2; ++k) dst[m][k] = *(const PG8_LAS bf16x8*)(lds + PG8_SA(b, h) + aoff + m * 2048 + k * 1024); } while (0)
; #define PG8_MMA(ai, bj, At, Bt) do { __builtin_amdgcn_s_setprio(1); _Pragma("unroll") for (int m = 0; m < 4; ++m) _Pragma("unroll") for (int n = 0; n < 2; ++n) _Pragma("unroll") for (int k = 0; k < 2; ++k) \
;         acc[ai][bj][m][n] = __builtin_amdgcn_mfma_f32_16x16x32_bf16(Bt[n][k], At[m][k], acc[ai][bj][m][n], 0, 0, 0); __builtin_amdgcn_s_setprio(0); } while (0)
; #define PG8_WAIT_V(n) asm volatile("s_waitcnt vmcnt(" #n ")" ::: "memory")
; #define PG8_WAIT_L(n) asm volatile("s_waitcnt lgkmcnt(" #n ")" ::: "memory")
; #define PG8_BAR __builtin_amdgcn_s_barrier()
; #define PG8_SCHED __builtin_amdgcn_sched_barrier(0)
; template <class Epi, class Sched, bool ALIGN_EPI = false, bool SP2 = false>
; __device__ __forceinline__ void gemm_phase(PG8_LAS unsigned char* lds, const Gemm g, const Sched& S, const Epi& E) {
;     ...
;         for (int t = 0; t < nt_u; t += 2) {
;             const bool last = (t == nt_u - 2);
;     ...
;             PG8_WAIT_V(8); PG8_WAIT_L(0); PG8_BAR; PG8_MMA(0, 0, At, B0); PG8_MMA(0, 1, At, B1); PG8_BAR; PG8_SCHED;
;             PG8_LDA(At, 1, 1); PG8_STAGE(PG8_SB(1, 0), b3, voffB); PG8_STAGE(PG8_SB(1, 1), b3 + hstep, voffB); PG8_STAGE(PG8_SA(1, 0), a3, voffA);
;             PG8_WAIT_V(8); PG8_WAIT_L(0); PG8_BAR; PG8_MMA(1, 0, At, B0); PG8_MMA(1, 1, At, B1); PG8_BAR; PG8_SCHED;
	s_add_i32 s20, s42, s3
	v_lshl_add_u64 v[174:175], v[174:175], 0, s[36:37]
	s_mov_b32 m0, s20
	ds_read_b128 v[192:195], v153 offset:49152
	ds_read_b128 v[196:199], v153 offset:50176
	ds_read_b128 v[200:203], v153 offset:51200
	ds_read_b128 v[204:207], v153 offset:52224
	ds_read_b128 v[212:215], v153 offset:53248
	ds_read_b128 v[216:219], v153 offset:54272
	ds_read_b128 v[220:223], v153 offset:55296
	ds_read_b128 v[224:227], v153 offset:56320
	global_load_lds_dwordx4 v[174:175], off
	s_add_i32 m0, s20, 0x2000
	s_add_u32 s20, s46, 0x18080
	v_lshl_add_u64 v[174:175], v[208:209], 0, s[36:37]
	s_addc_u32 s21, s47, 0
	s_add_i32 s42, s43, s3
	global_load_lds_dwordx4 v[174:175], off
	v_lshl_add_u64 v[174:175], s[20:21], 0, v[132:133]
	s_mov_b32 m0, s42
	s_nop 0
	global_load_lds_dwordx4 v[174:175], off
	v_lshl_add_u64 v[174:175], s[20:21], 0, v[128:129]
	s_add_i32 m0, s42, 0x2000
	s_nop 0
	global_load_lds_dwordx4 v[174:175], off
	v_lshl_add_u64 v[174:175], v[228:229], 0, s[36:37]
	s_mov_b32 m0, s10
	s_nop 0
	global_load_lds_dwordx4 v[174:175], off
	v_lshl_add_u64 v[174:175], v[230:231], 0, s[36:37]
	s_mov_b32 m0, s11
	s_nop 0
	global_load_lds_dwordx4 v[174:175], off
	s_waitcnt vmcnt(8)
	s_waitcnt lgkmcnt(0)
	s_barrier
	v_mfma_f32_16x16x32_bf16 v[60:63], v[144:147], v[192:195], v[60:63]
	v_mfma_f32_16x16x32_bf16 v[56:59], v[158:161], v[192:195], v[56:59]
	v_mfma_f32_16x16x32_bf16 v[52:55], v[144:147], v[200:203], v[52:55]
	v_mfma_f32_16x16x32_bf16 v[44:47], v[158:161], v[200:203], v[44:47]
	v_mfma_f32_16x16x32_bf16 v[36:39], v[144:147], v[212:215], v[36:39]
	v_mfma_f32_16x16x32_bf16 v[28:31], v[158:161], v[212:215], v[28:31]
	v_mfma_f32_16x16x32_bf16 v[20:23], v[144:147], v[220:223], v[20:23]
	v_mfma_f32_16x16x32_bf16 v[12:15], v[158:161], v[220:223], v[12:15]
	v_mfma_f32_16x16x32_bf16 v[60:63], v[154:157], v[196:199], v[60:63]
	v_mfma_f32_16x16x32_bf16 v[56:59], v[162:165], v[196:199], v[56:59]
	v_mfma_f32_16x16x32_bf16 v[52:55], v[154:157], v[204:207], v[52:55]
	v_mfma_f32_16x16x32_bf16 v[44:47], v[162:165], v[204:207], v[44:47]
	v_mfma_f32_16x16x32_bf16 v[36:39], v[154:157], v[216:219], v[36:39]
	v_mfma_f32_16x16x32_bf16 v[28:31], v[162:165], v[216:219], v[28:31]
	v_mfma_f32_16x16x32_bf16 v[20:23], v[154:157], v[224:227], v[20:23]
	v_mfma_f32_16x16x32_bf16 v[12:15], v[162:165], v[224:227], v[12:15]
	v_mfma_f32_16x16x32_bf16 v[48:51], v[166:169], v[192:195], v[48:51]
	v_mfma_f32_16x16x32_bf16 v[40:43], v[184:187], v[192:195], v[40:43]
	v_mfma_f32_16x16x32_bf16 v[32:35], v[166:169], v[200:203], v[32:35]
	v_mfma_f32_16x16x32_bf16 v[24:27], v[184:187], v[200:203], v[24:27]
	v_mfma_f32_16x16x32_bf16 v[16:19], v[166:169], v[212:215], v[16:19]
	v_mfma_f32_16x16x32_bf16 v[8:11], v[184:187], v[212:215], v[8:11]
	v_mfma_f32_16x16x32_bf16 v[4:7], v[166:169], v[220:223], v[4:7]
	v_mfma_f32_16x16x32_bf16 v[0:3], v[184:187], v[220:223], v[0:3]
	v_mfma_f32_16x16x32_bf16 v[48:51], v[170:173], v[196:199], v[48:51]
	v_mfma_f32_16x16x32_bf16 v[40:43], v[188:191], v[196:199], v[40:43]
	v_mfma_f32_16x16x32_bf16 v[32:35], v[170:173], v[204:207], v[32:35]
	v_mfma_f32_16x16x32_bf16 v[24:27], v[188:191], v[204:207], v[24:27]
	v_mfma_f32_16x16x32_bf16 v[16:19], v[170:173], v[216:219], v[16:19]
	v_mfma_f32_16x16x32_bf16 v[8:11], v[188:191], v[216:219], v[8:11]
	v_mfma_f32_16x16x32_bf16 v[4:7], v[170:173], v[224:227], v[4:7]
	v_mfma_f32_16x16x32_bf16 v[0:3], v[188:191], v[224:227], v[0:3]
	s_barrier
	s_add_i32 s83, s83, 2
	s_add_u32 s12, s12, 0x100
	s_addc_u32 s13, s13, 0
	s_cmp_gt_u32 s83, 3
	s_mov_b64 s[42:43], s[44:45]
	s_cbranch_scc0 .LBB0_312
	s_and_b64 vcc, exec, s[38:39]
	s_cbranch_vccz .LBB0_315
	s_barrier

; #define PG8_STAGE(bufoff, gbase, voff) do { _Pragma("unroll") for (int _i = 0; _i < 2; ++_i) \
;         __builtin_amdgcn_global_load_lds((const unsigned*)((const char*)(gbase) + (voff)[_i]), (PG8_LAS unsigned*)(lds + (bufoff) + ldsw + _i * 8192), 16, 0, 0); } while (0)
; #define PG8_LDA(dst, b, h) do { _Pragma("unroll") for (int m = 0; m < 4; ++m) _Pragma("unroll") for (int k = 0; k < 2; ++k) dst[m][k] = *(const PG8_LAS bf16x8*)(lds + PG8_SA(b, h) + aoff + m * 2048 + k * 1024); } while (0)
; #define PG8_LDB(dst, b, h) do { _Pragma("unroll") for (int n = 0; n < 2; ++n) _Pragma("unroll") for (int k = 0; k < 2; ++k) dst[n][k] = *(const PG8_LAS bf16x8*)(lds + PG8_SB(b, h) + boff + n * 2048 + k * 1024); } while (0)
; #define PG8_MMA(ai, bj, At, Bt) do { __builtin_amdgcn_s_setprio(1); _Pragma("unroll") for (int m = 0; m < 4; ++m) _Pragma("unroll") for (int n = 0; n < 2; ++n) _Pragma("unroll") for (int k = 0; k < 2; ++k) \
;         acc[ai][bj][m][n] = __builtin_amdgcn_mfma_f32_16x16x32_bf16(Bt[n][k], At[m][k], acc[ai][bj][m][n], 0, 0, 0); __builtin_amdgcn_s_setprio(0); } while (0)
; #define PG8_WAIT_V(n) asm volatile("s_waitcnt vmcnt(" #n ")" ::: "memory")
; #define PG8_WAIT_L(n) asm volatile("s_waitcnt lgkmcnt(" #n ")" ::: "memory")
; #define PG8_BAR __builtin_amdgcn_s_barrier()
; #define PG8_SCHED __builtin_amdgcn_sched_barrier(0)
; template <class Epi, class Sched, bool ALIGN_EPI = false, bool SP2 = false>
; __device__ __forceinline__ void gemm_phase(PG8_LAS unsigned char* lds, const Gemm g, const Sched& S, const Epi& E) {
;     ...
;             const bool last = (t == nt_u - 2);
;             const char* a1 = cA + (size_t)(t + 1) * kstep;
;             const char* a2 = last ? nA : cA + (size_t)(t + 2) * kstep; const char* b2 = last ? nB : cB + (size_t)(t + 2) * kstep;
;             const char* a3 = a2 + kstep; const char* b3 = b2 + kstep;
;             if (last && has_next) S.a_ready(nxt);
;             if constexpr (SP2) {
;             PG8_LDB(B0, 0, 0); PG8_LDB(B1, 0, 1); PG8_SCHED; PG8_LDA(At, 0, 0); PG8_STAGE(PG8_SA(1, 1), a1 + hstep, voffA);
;             PG8_WAIT_V(8); PG8_WAIT_L(0); PG8_BAR; PG8_MMA(0, 0, At, B0); PG8_MMA(0, 1, At, B1); PG8_BAR; PG8_SCHED;
;             PG8_LDA(At, 0, 1); PG8_STAGE(PG8_SB(0, 0), b2, voffB); PG8_STAGE(PG8_SB(0, 1), b2 + hstep, voffB); PG8_STAGE(PG8_SA(0, 0), a2, voffA);
.LBB0_328:
	s_add_u32 s48, s66, s13
	s_addc_u32 s49, s67, 0
	s_add_u32 s60, s48, 0x100
	s_addc_u32 s61, s49, 0
	s_and_b64 s[20:21], s[72:73], exec
	s_cselect_b32 s77, s7, s61
	s_cselect_b32 s76, s43, s60
	s_add_u32 s13, s62, s13
	s_addc_u32 s20, s63, 0
	s_add_u32 s13, s13, 0x100
	s_addc_u32 s60, s20, 0
	s_and_b64 s[20:21], s[72:73], exec
	s_cselect_b32 s79, s41, s60
	s_cselect_b32 s78, s12, s13
	s_add_u32 s82, s48, 0x10080
	s_addc_u32 s83, s49, 0
	s_add_i32 s64, s10, s3
	ds_read_b128 v[148:151], v145
	ds_read_b128 v[152:155], v145 offset:1024
	ds_read_b128 v[156:159], v145 offset:2048
	ds_read_b128 v[160:163], v145 offset:3072
	ds_read_b128 v[164:167], v146
	ds_read_b128 v[168:171], v146 offset:1024
	ds_read_b128 v[172:175], v146 offset:2048
	ds_read_b128 v[184:187], v146 offset:3072
	s_add_i32 m0, s51, 0xc000
	s_add_i32 s65, s51, 0xe000
	s_add_i32 s49, s64, 0x2000
	s_add_u32 s80, s78, 0x10000
	s_addc_u32 s81, s79, 0
	s_add_i32 s61, s11, s3
	s_add_i32 s60, s61, 0x2000
	s_add_i32 vcc_lo, 0, 0x18000
	s_add_i32 s21, 0, 0x1c000
	s_add_u32 s74, s76, 0x10000
	s_addc_u32 s75, s77, 0
	s_add_i32 s20, vcc_lo, s3
	s_add_i32 s48, s20, 0x2000
	s_add_u32 s72, s78, 0x10080
	s_addc_u32 s73, s79, 0
	s_add_i32 vcc_hi, s21, s3
	s_add_i32 s13, vcc_hi, 0x2000
	v_lshl_add_u64 v[140:141], s[82:83], 0, v[134:135]
	ds_read_b128 v[188:191], v147
	ds_read_b128 v[192:195], v147 offset:1024
	ds_read_b128 v[196:199], v147 offset:2048
	ds_read_b128 v[200:203], v147 offset:3072
	ds_read_b128 v[204:207], v147 offset:4096
	ds_read_b128 v[212:215], v147 offset:5120
	ds_read_b128 v[216:219], v147 offset:6144
	ds_read_b128 v[220:223], v147 offset:7168
	global_load_lds_dwordx4 v[140:141], off
	v_lshl_add_u64 v[140:141], s[82:83], 0, v[130:131]
	s_mov_b32 m0, s65
	s_nop 0
	global_load_lds_dwordx4 v[140:141], off
	s_waitcnt vmcnt(8)
	s_waitcnt lgkmcnt(0)
	s_barrier
	v_mfma_f32_16x16x32_bf16 v[124:127], v[148:151], v[188:191], v[124:127]
	v_mfma_f32_16x16x32_bf16 v[120:123], v[156:159], v[188:191], v[120:123]
	v_mfma_f32_16x16x32_bf16 v[116:119], v[148:151], v[196:199], v[116:119]
	v_mfma_f32_16x16x32_bf16 v[108:111], v[156:159], v[196:199], v[108:111]
	v_mfma_f32_16x16x32_bf16 v[100:103], v[148:151], v[204:207], v[100:103]
	v_mfma_f32_16x16x32_bf16 v[92:95], v[156:159], v[204:207], v[92:95]
	v_mfma_f32_16x16x32_bf16 v[84:87], v[148:151], v[216:219], v[84:87]
	v_mfma_f32_16x16x32_bf16 v[76:79], v[156:159], v[216:219], v[76:79]
	v_mfma_f32_16x16x32_bf16 v[124:127], v[152:155], v[192:195], v[124:127]
	v_mfma_f32_16x16x32_bf16 v[120:123], v[160:163], v[192:195], v[120:123]
	v_mfma_f32_16x16x32_bf16 v[116:119], v[152:155], v[200:203], v[116:119]
	v_mfma_f32_16x16x32_bf16 v[108:111], v[160:163], v[200:203], v[108:111]
	v_mfma_f32_16x16x32_bf16 v[100:103], v[152:155], v[212:215], v[100:103]
	v_mfma_f32_16x16x32_bf16 v[92:95], v[160:163], v[212:215], v[92:95]
	v_mfma_f32_16x16x32_bf16 v[84:87], v[152:155], v[220:223], v[84:87]
	v_mfma_f32_16x16x32_bf16 v[76:79], v[160:163], v[220:223], v[76:79]
	v_mfma_f32_16x16x32_bf16 v[112:115], v[164:167], v[188:191], v[112:115]
	v_mfma_f32_16x16x32_bf16 v[104:107], v[172:175], v[188:191], v[104:107]
	v_mfma_f32_16x16x32_bf16 v[96:99], v[164:167], v[196:199], v[96:99]
	v_mfma_f32_16x16x32_bf16 v[88:91], v[172:175], v[196:199], v[88:91]
	v_mfma_f32_16x16x32_bf16 v[80:83], v[164:167], v[204:207], v[80:83]
	v_mfma_f32_16x16x32_bf16 v[72:75], v[172:175], v[204:207], v[72:75]
	v_mfma_f32_16x16x32_bf16 v[68:71], v[164:167], v[216:219], v[68:71]
	v_mfma_f32_16x16x32_bf16 v[64:67], v[172:175], v[216:219], v[64:67]
	v_mfma_f32_16x16x32_bf16 v[112:115], v[168:171], v[192:195], v[112:115]
	v_mfma_f32_16x16x32_bf16 v[104:107], v[184:187], v[192:195], v[104:107]
	v_mfma_f32_16x16x32_bf16 v[96:99], v[168:171], v[200:203], v[96:99]
	v_mfma_f32_16x16x32_bf16 v[88:91], v[184:187], v[200:203], v[88:91]
	v_mfma_f32_16x16x32_bf16 v[80:83], v[168:171], v[212:215], v[80:83]
	v_mfma_f32_16x16x32_bf16 v[72:75], v[184:187], v[212:215], v[72:75]
	v_mfma_f32_16x16x32_bf16 v[68:71], v[168:171], v[220:223], v[68:71]
	v_mfma_f32_16x16x32_bf16 v[64:67], v[184:187], v[220:223], v[64:67]
	s_barrier
	s_mov_b32 m0, s64
	v_lshl_add_u64 v[140:141], s[78:79], 0, v[132:133]
	ds_read_b128 v[188:191], v147 offset:16384
	ds_read_b128 v[192:195], v147 offset:17408
	ds_read_b128 v[196:199], v147 offset:18432
	ds_read_b128 v[200:203], v147 offset:19456
	ds_read_b128 v[204:207], v147 offset:20480
	ds_read_b128 v[212:215], v147 offset:21504
	ds_read_b128 v[216:219], v147 offset:22528
	ds_read_b128 v[220:223], v147 offset:23552
	global_load_lds_dwordx4 v[140:141], off
	v_lshl_add_u64 v[208:209], s[78:79], 0, v[128:129]
	s_mov_b32 m0, s49
	v_lshl_add_u64 v[224:225], s[80:81], 0, v[132:133]
	global_load_lds_dwordx4 v[208:209], off
	s_mov_b32 m0, s61
	v_lshl_add_u64 v[226:227], s[76:77], 0, v[130:131]
	global_load_lds_dwordx4 v[224:225], off
	v_lshl_add_u64 v[224:225], s[80:81], 0, v[128:129]
	s_mov_b32 m0, s60
	s_nop 0
	global_load_lds_dwordx4 v[224:225], off
	v_lshl_add_u64 v[224:225], s[76:77], 0, v[134:135]
	s_mov_b32 m0, s51
	s_nop 0
	global_load_lds_dwordx4 v[224:225], off
	s_mov_b32 m0, s91
	s_nop 0
	global_load_lds_dwordx4 v[226:227], off
	s_waitcnt vmcnt(8)
	s_waitcnt lgkmcnt(0)
	s_barrier
; #define PG8_STAGE(bufoff, gbase, voff) do { _Pragma("unroll") for (int _i = 0; _i < 2; ++_i) \
;         __builtin_amdgcn_global_load_lds((const unsigned*)((const char*)(gbase) + (voff)[_i]), (PG8_LAS unsigned*)(lds + (bufoff) + ldsw + _i * 8192), 16, 0, 0); } while (0)
; #define PG8_LDA(dst, b, h) do { _Pragma("unroll") for (int m = 0; m < 4; ++m) _Pragma("unroll") for (int k = 0; k < 2; ++k) dst[m][k] = *(const PG8_LAS bf16x8*)(lds + PG8_SA(b, h) + aoff + m * 2048 + k * 1024); } while (0)
; #define PG8_LDB(dst, b, h) do { _Pragma("unroll") for (int n = 0; n < 2; ++n) _Pragma("unroll") for (int k = 0; k < 2; ++k) dst[n][k] = *(const PG8_LAS bf16x8*)(lds + PG8_SB(b, h) + boff + n * 2048 + k * 1024); } while (0)
; #define PG8_MMA(ai, bj, At, Bt) do { __builtin_amdgcn_s_setprio(1); _Pragma("unroll") for (int m = 0; m < 4; ++m) _Pragma("unroll") for (int n = 0; n < 2; ++n) _Pragma("unroll") for (int k = 0; k < 2; ++k) \
;         acc[ai][bj][m][n] = __builtin_amdgcn_mfma_f32_16x16x32_bf16(Bt[n][k], At[m][k], acc[ai][bj][m][n], 0, 0, 0); __builtin_amdgcn_s_setprio(0); } while (0)
; #define PG8_WAIT_V(n) asm volatile("s_waitcnt vmcnt(" #n ")" ::: "memory")
; #define PG8_WAIT_L(n) asm volatile("s_waitcnt lgkmcnt(" #n ")" ::: "memory")
; #define PG8_BAR __builtin_amdgcn_s_barrier()
; #define PG8_SCHED __builtin_amdgcn_sched_barrier(0)
; template <class Epi, class Sched, bool ALIGN_EPI = false, bool SP2 = false>
; __device__ __forceinline__ void gemm_phase(PG8_LAS unsigned char* lds, const Gemm g, const Sched& S, const Epi& E) {
;     ...
;             PG8_WAIT_V(8); PG8_WAIT_L(0); PG8_BAR; PG8_MMA(0, 0, At, B0); PG8_MMA(0, 1, At, B1); PG8_BAR; PG8_SCHED;
;             PG8_LDA(At, 0, 1); PG8_STAGE(PG8_SB(0, 0), b2, voffB); PG8_STAGE(PG8_SB(0, 1), b2 + hstep, voffB); PG8_STAGE(PG8_SA(0, 0), a2, voffA);
;             PG8_WAIT_V(8); PG8_WAIT_L(0); PG8_BAR; PG8_MMA(1, 0, At, B0); PG8_MMA(1, 1, At, B1); PG8_BAR; PG8_SCHED;
;             PG8_LDB(B0, 1, 0); PG8_LDB(B1, 1, 1); PG8_SCHED; PG8_LDA(At, 1, 0); PG8_STAGE(PG8_SA(0, 1), a2 + hstep, voffA);
;             PG8_WAIT_V(8); PG8_WAIT_L(0); PG8_BAR; PG8_MMA(0, 0, At, B0); PG8_MMA(0, 1, At, B1); PG8_BAR; PG8_SCHED;
	v_mfma_f32_16x16x32_bf16 v[60:63], v[148:151], v[188:191], v[60:63]
	v_mfma_f32_16x16x32_bf16 v[56:59], v[156:159], v[188:191], v[56:59]
	v_mfma_f32_16x16x32_bf16 v[52:55], v[148:151], v[196:199], v[52:55]
	v_mfma_f32_16x16x32_bf16 v[44:47], v[156:159], v[196:199], v[44:47]
	v_mfma_f32_16x16x32_bf16 v[36:39], v[148:151], v[204:207], v[36:39]
	v_mfma_f32_16x16x32_bf16 v[28:31], v[156:159], v[204:207], v[28:31]
	v_mfma_f32_16x16x32_bf16 v[20:23], v[148:151], v[216:219], v[20:23]
	v_mfma_f32_16x16x32_bf16 v[12:15], v[156:159], v[216:219], v[12:15]
	v_mfma_f32_16x16x32_bf16 v[60:63], v[152:155], v[192:195], v[60:63]
	v_mfma_f32_16x16x32_bf16 v[56:59], v[160:163], v[192:195], v[56:59]
	v_mfma_f32_16x16x32_bf16 v[52:55], v[152:155], v[200:203], v[52:55]
	v_mfma_f32_16x16x32_bf16 v[44:47], v[160:163], v[200:203], v[44:47]
	v_mfma_f32_16x16x32_bf16 v[36:39], v[152:155], v[212:215], v[36:39]
	v_mfma_f32_16x16x32_bf16 v[28:31], v[160:163], v[212:215], v[28:31]
	v_mfma_f32_16x16x32_bf16 v[20:23], v[152:155], v[220:223], v[20:23]
	v_mfma_f32_16x16x32_bf16 v[12:15], v[160:163], v[220:223], v[12:15]
	v_mfma_f32_16x16x32_bf16 v[48:51], v[164:167], v[188:191], v[48:51]
	v_mfma_f32_16x16x32_bf16 v[40:43], v[172:175], v[188:191], v[40:43]
	v_mfma_f32_16x16x32_bf16 v[32:35], v[164:167], v[196:199], v[32:35]
	v_mfma_f32_16x16x32_bf16 v[24:27], v[172:175], v[196:199], v[24:27]
	v_mfma_f32_16x16x32_bf16 v[16:19], v[164:167], v[204:207], v[16:19]
	v_mfma_f32_16x16x32_bf16 v[8:11], v[172:175], v[204:207], v[8:11]
	v_mfma_f32_16x16x32_bf16 v[4:7], v[164:167], v[216:219], v[4:7]
	v_mfma_f32_16x16x32_bf16 v[0:3], v[172:175], v[216:219], v[0:3]
	v_mfma_f32_16x16x32_bf16 v[48:51], v[168:171], v[192:195], v[48:51]
	v_mfma_f32_16x16x32_bf16 v[40:43], v[184:187], v[192:195], v[40:43]
	v_mfma_f32_16x16x32_bf16 v[32:35], v[168:171], v[200:203], v[32:35]
	v_mfma_f32_16x16x32_bf16 v[24:27], v[184:187], v[200:203], v[24:27]
	v_mfma_f32_16x16x32_bf16 v[16:19], v[168:171], v[212:215], v[16:19]
	v_mfma_f32_16x16x32_bf16 v[8:11], v[184:187], v[212:215], v[8:11]
	v_mfma_f32_16x16x32_bf16 v[4:7], v[168:171], v[220:223], v[4:7]
	v_mfma_f32_16x16x32_bf16 v[0:3], v[184:187], v[220:223], v[0:3]
	s_barrier
	v_add_u32_e32 v160, vcc_lo, v143
	v_add_u32_e32 v177, s21, v143
	ds_read_b128 v[148:151], v160
	ds_read_b128 v[152:155], v160 offset:1024
	ds_read_b128 v[156:159], v160 offset:2048
	ds_read_b128 v[160:163], v160 offset:3072
	ds_read_b128 v[164:167], v177
	ds_read_b128 v[168:171], v177 offset:1024
	ds_read_b128 v[172:175], v177 offset:2048
	ds_read_b128 v[184:187], v177 offset:3072
	s_mov_b32 m0, s92
	v_lshl_add_u64 v[228:229], s[74:75], 0, v[134:135]
	ds_read_b128 v[188:191], v147 offset:32768
	ds_read_b128 v[192:195], v147 offset:33792
	ds_read_b128 v[196:199], v147 offset:34816
	ds_read_b128 v[200:203], v147 offset:35840
	ds_read_b128 v[204:207], v147 offset:36864
	ds_read_b128 v[212:215], v147 offset:37888
	ds_read_b128 v[216:219], v147 offset:38912
	ds_read_b128 v[220:223], v147 offset:39936
	global_load_lds_dwordx4 v[228:229], off
	v_lshl_add_u64 v[228:229], s[74:75], 0, v[130:131]
	s_mov_b32 m0, s93
	s_nop 0
	global_load_lds_dwordx4 v[228:229], off
	s_waitcnt vmcnt(8)
	s_waitcnt lgkmcnt(0)
	s_barrier
	v_mfma_f32_16x16x32_bf16 v[124:127], v[148:151], v[188:191], v[124:127]
	v_mfma_f32_16x16x32_bf16 v[120:123], v[156:159], v[188:191], v[120:123]
	v_mfma_f32_16x16x32_bf16 v[116:119], v[148:151], v[196:199], v[116:119]
	v_mfma_f32_16x16x32_bf16 v[108:111], v[156:159], v[196:199], v[108:111]
	v_mfma_f32_16x16x32_bf16 v[100:103], v[148:151], v[204:207], v[100:103]
	v_mfma_f32_16x16x32_bf16 v[92:95], v[156:159], v[204:207], v[92:95]
	v_mfma_f32_16x16x32_bf16 v[84:87], v[148:151], v[216:219], v[84:87]
	v_mfma_f32_16x16x32_bf16 v[76:79], v[156:159], v[216:219], v[76:79]
	v_mfma_f32_16x16x32_bf16 v[124:127], v[152:155], v[192:195], v[124:127]
	v_mfma_f32_16x16x32_bf16 v[120:123], v[160:163], v[192:195], v[120:123]
	v_mfma_f32_16x16x32_bf16 v[116:119], v[152:155], v[200:203], v[116:119]
	v_mfma_f32_16x16x32_bf16 v[108:111], v[160:163], v[200:203], v[108:111]
	v_mfma_f32_16x16x32_bf16 v[100:103], v[152:155], v[212:215], v[100:103]
	v_mfma_f32_16x16x32_bf16 v[92:95], v[160:163], v[212:215], v[92:95]
	v_mfma_f32_16x16x32_bf16 v[84:87], v[152:155], v[220:223], v[84:87]
	v_mfma_f32_16x16x32_bf16 v[76:79], v[160:163], v[220:223], v[76:79]
	v_mfma_f32_16x16x32_bf16 v[112:115], v[164:167], v[188:191], v[112:115]
	v_mfma_f32_16x16x32_bf16 v[104:107], v[172:175], v[188:191], v[104:107]
	v_mfma_f32_16x16x32_bf16 v[96:99], v[164:167], v[196:199], v[96:99]
	v_mfma_f32_16x16x32_bf16 v[88:91], v[172:175], v[196:199], v[88:91]
	v_mfma_f32_16x16x32_bf16 v[80:83], v[164:167], v[204:207], v[80:83]
	v_mfma_f32_16x16x32_bf16 v[72:75], v[172:175], v[204:207], v[72:75]
	v_mfma_f32_16x16x32_bf16 v[68:71], v[164:167], v[216:219], v[68:71]
	v_mfma_f32_16x16x32_bf16 v[64:67], v[172:175], v[216:219], v[64:67]
	v_mfma_f32_16x16x32_bf16 v[112:115], v[168:171], v[192:195], v[112:115]
	v_mfma_f32_16x16x32_bf16 v[104:107], v[184:187], v[192:195], v[104:107]
	v_mfma_f32_16x16x32_bf16 v[96:99], v[168:171], v[200:203], v[96:99]
	v_mfma_f32_16x16x32_bf16 v[88:91], v[184:187], v[200:203], v[88:91]
	v_mfma_f32_16x16x32_bf16 v[80:83], v[168:171], v[212:215], v[80:83]
	v_mfma_f32_16x16x32_bf16 v[72:75], v[184:187], v[212:215], v[72:75]
	v_mfma_f32_16x16x32_bf16 v[68:71], v[168:171], v[220:223], v[68:71]
	v_mfma_f32_16x16x32_bf16 v[64:67], v[184:187], v[220:223], v[64:67]
	s_barrier
; #define PG8_STAGE(bufoff, gbase, voff) do { _Pragma("unroll") for (int _i = 0; _i < 2; ++_i) \
;         __builtin_amdgcn_global_load_lds((const unsigned*)((const char*)(gbase) + (voff)[_i]), (PG8_LAS unsigned*)(lds + (bufoff) + ldsw + _i * 8192), 16, 0, 0); } while (0)
; #define PG8_LDA(dst, b, h) do { _Pragma("unroll") for (int m = 0; m < 4; ++m) _Pragma("unroll") for (int k = 0; k < 2; ++k) dst[m][k] = *(const PG8_LAS bf16x8*)(lds + PG8_SA(b, h) + aoff + m * 2048 + k * 1024); } while (0)
; #define PG8_MMA(ai, bj, At, Bt) do { __builtin_amdgcn_s_setprio(1); _Pragma("unroll") for (int m = 0; m < 4; ++m) _Pragma("unroll") for (int n = 0; n < 2; ++n) _Pragma("unroll") for (int k = 0; k < 2; ++k) \
;         acc[ai][bj][m][n] = __builtin_amdgcn_mfma_f32_16x16x32_bf16(Bt[n][k], At[m][k], acc[ai][bj][m][n], 0, 0, 0); __builtin_amdgcn_s_setprio(0); } while (0)
; #define PG8_WAIT_V(n) asm volatile("s_waitcnt vmcnt(" #n ")" ::: "memory")
; #define PG8_WAIT_L(n) asm volatile("s_waitcnt lgkmcnt(" #n ")" ::: "memory")
; #define PG8_BAR __builtin_amdgcn_s_barrier()
; #define PG8_SCHED __builtin_amdgcn_sched_barrier(0)
; template <class Epi, class Sched, bool ALIGN_EPI = false, bool SP2 = false>
; __device__ __forceinline__ void gemm_phase(PG8_LAS unsigned char* lds, const Gemm g, const Sched& S, const Epi& E) {
;     ...
;         for (int t = 0; t < nt_u; t += 2) {
;             const bool last = (t == nt_u - 2);
;     ...
;             PG8_WAIT_V(8); PG8_WAIT_L(0); PG8_BAR; PG8_MMA(0, 0, At, B0); PG8_MMA(0, 1, At, B1); PG8_BAR; PG8_SCHED;
;             PG8_LDA(At, 1, 1); PG8_STAGE(PG8_SB(1, 0), b3, voffB); PG8_STAGE(PG8_SB(1, 1), b3 + hstep, voffB); PG8_STAGE(PG8_SA(1, 0), a3, voffA);
;             PG8_WAIT_V(8); PG8_WAIT_L(0); PG8_BAR; PG8_MMA(1, 0, At, B0); PG8_MMA(1, 1, At, B1); PG8_BAR; PG8_SCHED;
	s_mov_b32 m0, s20
	v_lshl_add_u64 v[140:141], v[140:141], 0, s[36:37]
	ds_read_b128 v[188:191], v147 offset:49152
	ds_read_b128 v[192:195], v147 offset:50176
	ds_read_b128 v[196:199], v147 offset:51200
	ds_read_b128 v[200:203], v147 offset:52224
	ds_read_b128 v[204:207], v147 offset:53248
	ds_read_b128 v[212:215], v147 offset:54272
	ds_read_b128 v[216:219], v147 offset:55296
	ds_read_b128 v[220:223], v147 offset:56320
	global_load_lds_dwordx4 v[140:141], off
	v_lshl_add_u64 v[140:141], v[208:209], 0, s[36:37]
	s_mov_b32 m0, s48
	s_nop 0
	global_load_lds_dwordx4 v[140:141], off
	v_lshl_add_u64 v[140:141], s[72:73], 0, v[132:133]
	s_mov_b32 m0, vcc_hi
	s_nop 0
	global_load_lds_dwordx4 v[140:141], off
	v_lshl_add_u64 v[140:141], s[72:73], 0, v[128:129]
	s_mov_b32 m0, s13
	s_nop 0
	global_load_lds_dwordx4 v[140:141], off
	v_lshl_add_u64 v[140:141], v[224:225], 0, s[36:37]
	s_mov_b32 m0, s95
	s_nop 0
	global_load_lds_dwordx4 v[140:141], off
	v_lshl_add_u64 v[140:141], v[226:227], 0, s[36:37]
	s_mov_b32 m0, s96
	s_nop 0
	global_load_lds_dwordx4 v[140:141], off
	s_waitcnt vmcnt(8)
	s_waitcnt lgkmcnt(0)
	s_barrier
	v_mfma_f32_16x16x32_bf16 v[60:63], v[148:151], v[188:191], v[60:63]
	v_mfma_f32_16x16x32_bf16 v[56:59], v[156:159], v[188:191], v[56:59]
	v_mfma_f32_16x16x32_bf16 v[52:55], v[148:151], v[196:199], v[52:55]
	v_mfma_f32_16x16x32_bf16 v[44:47], v[156:159], v[196:199], v[44:47]
	v_mfma_f32_16x16x32_bf16 v[36:39], v[148:151], v[204:207], v[36:39]
	v_mfma_f32_16x16x32_bf16 v[28:31], v[156:159], v[204:207], v[28:31]
	v_mfma_f32_16x16x32_bf16 v[20:23], v[148:151], v[216:219], v[20:23]
	v_mfma_f32_16x16x32_bf16 v[12:15], v[156:159], v[216:219], v[12:15]
	v_mfma_f32_16x16x32_bf16 v[60:63], v[152:155], v[192:195], v[60:63]
	v_mfma_f32_16x16x32_bf16 v[56:59], v[160:163], v[192:195], v[56:59]
	v_mfma_f32_16x16x32_bf16 v[52:55], v[152:155], v[200:203], v[52:55]
	v_mfma_f32_16x16x32_bf16 v[44:47], v[160:163], v[200:203], v[44:47]
	v_mfma_f32_16x16x32_bf16 v[36:39], v[152:155], v[212:215], v[36:39]
	v_mfma_f32_16x16x32_bf16 v[28:31], v[160:163], v[212:215], v[28:31]
	v_mfma_f32_16x16x32_bf16 v[20:23], v[152:155], v[220:223], v[20:23]
	v_mfma_f32_16x16x32_bf16 v[12:15], v[160:163], v[220:223], v[12:15]
	v_mfma_f32_16x16x32_bf16 v[48:51], v[164:167], v[188:191], v[48:51]
	v_mfma_f32_16x16x32_bf16 v[40:43], v[172:175], v[188:191], v[40:43]
	v_mfma_f32_16x16x32_bf16 v[32:35], v[164:167], v[196:199], v[32:35]
	v_mfma_f32_16x16x32_bf16 v[24:27], v[172:175], v[196:199], v[24:27]
	v_mfma_f32_16x16x32_bf16 v[16:19], v[164:167], v[204:207], v[16:19]
	v_mfma_f32_16x16x32_bf16 v[8:11], v[172:175], v[204:207], v[8:11]
	v_mfma_f32_16x16x32_bf16 v[4:7], v[164:167], v[216:219], v[4:7]
	v_mfma_f32_16x16x32_bf16 v[0:3], v[172:175], v[216:219], v[0:3]
	v_mfma_f32_16x16x32_bf16 v[48:51], v[168:171], v[192:195], v[48:51]
	v_mfma_f32_16x16x32_bf16 v[40:43], v[184:187], v[192:195], v[40:43]
	v_mfma_f32_16x16x32_bf16 v[32:35], v[168:171], v[200:203], v[32:35]
	v_mfma_f32_16x16x32_bf16 v[24:27], v[184:187], v[200:203], v[24:27]
	v_mfma_f32_16x16x32_bf16 v[16:19], v[168:171], v[212:215], v[16:19]
	v_mfma_f32_16x16x32_bf16 v[8:11], v[184:187], v[212:215], v[8:11]
	v_mfma_f32_16x16x32_bf16 v[4:7], v[168:171], v[220:223], v[4:7]
	v_mfma_f32_16x16x32_bf16 v[0:3], v[184:187], v[220:223], v[0:3]
	s_barrier
	s_movk_i32 s13, 0x100
	s_andn2_b64 vcc, exec, s[70:71]
	s_mov_b64 s[72:73], -1
	s_mov_b64 s[70:71], 0
	s_cbranch_vccz .LBB0_328
	s_and_b64 vcc, exec, s[38:39]
	s_cbranch_vccz .LBB0_331
	s_barrier

; #define PG8_STAGE(bufoff, gbase, voff) do { _Pragma("unroll") for (int _i = 0; _i < 2; ++_i) \
;         __builtin_amdgcn_global_load_lds((const unsigned*)((const char*)(gbase) + (voff)[_i]), (PG8_LAS unsigned*)(lds + (bufoff) + ldsw + _i * 8192), 16, 0, 0); } while (0)
; #define PG8_LDA(dst, b, h) do { _Pragma("unroll") for (int m = 0; m < 4; ++m) _Pragma("unroll") for (int k = 0; k < 2; ++k) dst[m][k] = *(const PG8_LAS bf16x8*)(lds + PG8_SA(b, h) + aoff + m * 2048 + k * 1024); } while (0)
; #define PG8_LDB(dst, b, h) do { _Pragma("unroll") for (int n = 0; n < 2; ++n) _Pragma("unroll") for (int k = 0; k < 2; ++k) dst[n][k] = *(const PG8_LAS bf16x8*)(lds + PG8_SB(b, h) + boff + n * 2048 + k * 1024); } while (0)
; #define PG8_MMA(ai, bj, At, Bt) do { __builtin_amdgcn_s_setprio(1); _Pragma("unroll") for (int m = 0; m < 4; ++m) _Pragma("unroll") for (int n = 0; n < 2; ++n) _Pragma("unroll") for (int k = 0; k < 2; ++k) \
;         acc[ai][bj][m][n] = __builtin_amdgcn_mfma_f32_16x16x32_bf16(Bt[n][k], At[m][k], acc[ai][bj][m][n], 0, 0, 0); __builtin_amdgcn_s_setprio(0); } while (0)
; #define PG8_WAIT_V(n) asm volatile("s_waitcnt vmcnt(" #n ")" ::: "memory")
; #define PG8_WAIT_L(n) asm volatile("s_waitcnt lgkmcnt(" #n ")" ::: "memory")
; #define PG8_BAR __builtin_amdgcn_s_barrier()
; #define PG8_SCHED __builtin_amdgcn_sched_barrier(0)
; template <class Epi, class Sched, bool ALIGN_EPI = false, bool SP2 = false>
; __device__ __forceinline__ void gemm_phase(PG8_LAS unsigned char* lds, const Gemm g, const Sched& S, const Epi& E) {
;     ...
;             const bool last = (t == nt_u - 2);
;             const char* a1 = cA + (size_t)(t + 1) * kstep;
;             const char* a2 = last ? nA : cA + (size_t)(t + 2) * kstep; const char* b2 = last ? nB : cB + (size_t)(t + 2) * kstep;
;             const char* a3 = a2 + kstep; const char* b3 = b2 + kstep;
;             if (last && has_next) S.a_ready(nxt);
;             if constexpr (SP2) {
;             PG8_LDB(B0, 0, 0); PG8_LDB(B1, 0, 1); PG8_SCHED; PG8_LDA(At, 0, 0); PG8_STAGE(PG8_SA(1, 1), a1 + hstep, voffA);
;             PG8_WAIT_V(8); PG8_WAIT_L(0); PG8_BAR; PG8_MMA(0, 0, At, B0); PG8_MMA(0, 1, At, B1); PG8_BAR; PG8_SCHED;
;             PG8_LDA(At, 0, 1); PG8_STAGE(PG8_SB(0, 0), b2, voffB); PG8_STAGE(PG8_SB(0, 1), b2 + hstep, voffB); PG8_STAGE(PG8_SA(0, 0), a2, voffA);
.LBB0_543:
	ds_read_b128 v[128:131], v163
	ds_read_b128 v[132:135], v163 offset:1024
	ds_read_b128 v[136:139], v163 offset:2048
	ds_read_b128 v[140:143], v163 offset:3072
	ds_read_b128 v[156:159], v164
	ds_read_b128 v[166:169], v164 offset:1024
	ds_read_b128 v[170:173], v164 offset:2048
	ds_read_b128 v[182:185], v164 offset:3072
	s_add_u32 s20, s46, 0xfffc0080
	s_addc_u32 s21, s47, -1
	s_cmp_eq_u32 s79, 12
	s_cselect_b32 s51, s12, s21
	s_cselect_b32 s50, s13, s20
	s_cselect_b32 s49, s37, s78
	s_cselect_b32 s48, s39, s45
	v_lshl_add_u64 v[174:175], s[46:47], 0, v[148:149]
	s_add_i32 m0, s63, 0xc000
	ds_read_b128 v[186:189], v165
	ds_read_b128 v[190:193], v165 offset:1024
	ds_read_b128 v[194:197], v165 offset:2048
	ds_read_b128 v[198:201], v165 offset:3072
	ds_read_b128 v[202:205], v165 offset:4096
	ds_read_b128 v[206:209], v165 offset:5120
	ds_read_b128 v[212:215], v165 offset:6144
	ds_read_b128 v[216:219], v165 offset:7168
	global_load_lds_dwordx4 v[174:175], off
	v_lshl_add_u64 v[174:175], s[46:47], 0, v[150:151]
	s_add_i32 m0, s63, 0xe000
	s_nop 0
	global_load_lds_dwordx4 v[174:175], off
	s_waitcnt vmcnt(8)
	s_waitcnt lgkmcnt(0)
	s_barrier
	v_mfma_f32_16x16x32_bf16 v[124:127], v[128:131], v[186:189], v[124:127]
	v_mfma_f32_16x16x32_bf16 v[120:123], v[136:139], v[186:189], v[120:123]
	v_mfma_f32_16x16x32_bf16 v[112:115], v[128:131], v[194:197], v[112:115]
	v_mfma_f32_16x16x32_bf16 v[108:111], v[136:139], v[194:197], v[108:111]
	v_mfma_f32_16x16x32_bf16 v[96:99], v[128:131], v[202:205], v[96:99]
	v_mfma_f32_16x16x32_bf16 v[92:95], v[136:139], v[202:205], v[92:95]
	v_mfma_f32_16x16x32_bf16 v[80:83], v[128:131], v[212:215], v[80:83]
	v_mfma_f32_16x16x32_bf16 v[76:79], v[136:139], v[212:215], v[76:79]
	v_mfma_f32_16x16x32_bf16 v[124:127], v[132:135], v[190:193], v[124:127]
	v_mfma_f32_16x16x32_bf16 v[120:123], v[140:143], v[190:193], v[120:123]
	v_mfma_f32_16x16x32_bf16 v[112:115], v[132:135], v[198:201], v[112:115]
	v_mfma_f32_16x16x32_bf16 v[108:111], v[140:143], v[198:201], v[108:111]
	v_mfma_f32_16x16x32_bf16 v[96:99], v[132:135], v[206:209], v[96:99]
	v_mfma_f32_16x16x32_bf16 v[92:95], v[140:143], v[206:209], v[92:95]
	v_mfma_f32_16x16x32_bf16 v[80:83], v[132:135], v[216:219], v[80:83]
	v_mfma_f32_16x16x32_bf16 v[76:79], v[140:143], v[216:219], v[76:79]
	v_mfma_f32_16x16x32_bf16 v[116:119], v[156:159], v[186:189], v[116:119]
	v_mfma_f32_16x16x32_bf16 v[104:107], v[170:173], v[186:189], v[104:107]
	v_mfma_f32_16x16x32_bf16 v[100:103], v[156:159], v[194:197], v[100:103]
	v_mfma_f32_16x16x32_bf16 v[88:91], v[170:173], v[194:197], v[88:91]
	v_mfma_f32_16x16x32_bf16 v[84:87], v[156:159], v[202:205], v[84:87]
	v_mfma_f32_16x16x32_bf16 v[72:75], v[170:173], v[202:205], v[72:75]
	v_mfma_f32_16x16x32_bf16 v[68:71], v[156:159], v[212:215], v[68:71]
	v_mfma_f32_16x16x32_bf16 v[64:67], v[170:173], v[212:215], v[64:67]
	v_mfma_f32_16x16x32_bf16 v[116:119], v[166:169], v[190:193], v[116:119]
	v_mfma_f32_16x16x32_bf16 v[104:107], v[182:185], v[190:193], v[104:107]
	v_mfma_f32_16x16x32_bf16 v[100:103], v[166:169], v[198:201], v[100:103]
	v_mfma_f32_16x16x32_bf16 v[88:91], v[182:185], v[198:201], v[88:91]
	v_mfma_f32_16x16x32_bf16 v[84:87], v[166:169], v[206:209], v[84:87]
	v_mfma_f32_16x16x32_bf16 v[72:75], v[182:185], v[206:209], v[72:75]
	v_mfma_f32_16x16x32_bf16 v[68:71], v[166:169], v[216:219], v[68:71]
	v_mfma_f32_16x16x32_bf16 v[64:67], v[182:185], v[216:219], v[64:67]
	s_barrier
	s_add_i32 s20, s75, s3
	v_lshl_add_u64 v[174:175], s[48:49], 0, v[146:147]
	s_mov_b32 m0, s20
	ds_read_b128 v[186:189], v165 offset:16384
	ds_read_b128 v[190:193], v165 offset:17408
	ds_read_b128 v[194:197], v165 offset:18432
	ds_read_b128 v[198:201], v165 offset:19456
	ds_read_b128 v[202:205], v165 offset:20480
	ds_read_b128 v[206:209], v165 offset:21504
	ds_read_b128 v[212:215], v165 offset:22528
	ds_read_b128 v[216:219], v165 offset:23552
	global_load_lds_dwordx4 v[174:175], off
	s_add_i32 m0, s20, 0x2000
	s_add_u32 s20, s48, 0x40000
	v_lshl_add_u64 v[220:221], s[48:49], 0, v[144:145]
	s_addc_u32 s21, s49, 0
	s_add_i32 s60, s76, s3
	global_load_lds_dwordx4 v[220:221], off
	v_lshl_add_u64 v[222:223], s[20:21], 0, v[146:147]
	s_mov_b32 m0, s60
	v_lshl_add_u64 v[224:225], s[50:51], 0, v[144:145]
	global_load_lds_dwordx4 v[222:223], off
	v_lshl_add_u64 v[222:223], s[20:21], 0, v[144:145]
	s_add_i32 m0, s60, 0x2000
	s_nop 0
	global_load_lds_dwordx4 v[222:223], off
	v_lshl_add_u64 v[222:223], s[50:51], 0, v[146:147]
	s_mov_b32 m0, s63
	s_nop 0
	global_load_lds_dwordx4 v[222:223], off
	s_mov_b32 m0, s66
	s_nop 0
	global_load_lds_dwordx4 v[224:225], off
	s_waitcnt vmcnt(8)
	s_waitcnt lgkmcnt(0)
	s_barrier
; #define PG8_STAGE(bufoff, gbase, voff) do { _Pragma("unroll") for (int _i = 0; _i < 2; ++_i) \
;         __builtin_amdgcn_global_load_lds((const unsigned*)((const char*)(gbase) + (voff)[_i]), (PG8_LAS unsigned*)(lds + (bufoff) + ldsw + _i * 8192), 16, 0, 0); } while (0)
; #define PG8_LDA(dst, b, h) do { _Pragma("unroll") for (int m = 0; m < 4; ++m) _Pragma("unroll") for (int k = 0; k < 2; ++k) dst[m][k] = *(const PG8_LAS bf16x8*)(lds + PG8_SA(b, h) + aoff + m * 2048 + k * 1024); } while (0)
; #define PG8_LDB(dst, b, h) do { _Pragma("unroll") for (int n = 0; n < 2; ++n) _Pragma("unroll") for (int k = 0; k < 2; ++k) dst[n][k] = *(const PG8_LAS bf16x8*)(lds + PG8_SB(b, h) + boff + n * 2048 + k * 1024); } while (0)
; #define PG8_MMA(ai, bj, At, Bt) do { __builtin_amdgcn_s_setprio(1); _Pragma("unroll") for (int m = 0; m < 4; ++m) _Pragma("unroll") for (int n = 0; n < 2; ++n) _Pragma("unroll") for (int k = 0; k < 2; ++k) \
;         acc[ai][bj][m][n] = __builtin_amdgcn_mfma_f32_16x16x32_bf16(Bt[n][k], At[m][k], acc[ai][bj][m][n], 0, 0, 0); __builtin_amdgcn_s_setprio(0); } while (0)
; #define PG8_WAIT_V(n) asm volatile("s_waitcnt vmcnt(" #n ")" ::: "memory")
; #define PG8_WAIT_L(n) asm volatile("s_waitcnt lgkmcnt(" #n ")" ::: "memory")
; #define PG8_BAR __builtin_amdgcn_s_barrier()
; #define PG8_SCHED __builtin_amdgcn_sched_barrier(0)
; template <class Epi, class Sched, bool ALIGN_EPI = false, bool SP2 = false>
; __device__ __forceinline__ void gemm_phase(PG8_LAS unsigned char* lds, const Gemm g, const Sched& S, const Epi& E) {
;     ...
;             PG8_WAIT_V(8); PG8_WAIT_L(0); PG8_BAR; PG8_MMA(0, 0, At, B0); PG8_MMA(0, 1, At, B1); PG8_BAR; PG8_SCHED;
;             PG8_LDA(At, 0, 1); PG8_STAGE(PG8_SB(0, 0), b2, voffB); PG8_STAGE(PG8_SB(0, 1), b2 + hstep, voffB); PG8_STAGE(PG8_SA(0, 0), a2, voffA);
;             PG8_WAIT_V(8); PG8_WAIT_L(0); PG8_BAR; PG8_MMA(1, 0, At, B0); PG8_MMA(1, 1, At, B1); PG8_BAR; PG8_SCHED;
;             PG8_LDB(B0, 1, 0); PG8_LDB(B1, 1, 1); PG8_SCHED; PG8_LDA(At, 1, 0); PG8_STAGE(PG8_SA(0, 1), a2 + hstep, voffA);
;             PG8_WAIT_V(8); PG8_WAIT_L(0); PG8_BAR; PG8_MMA(0, 0, At, B0); PG8_MMA(0, 1, At, B1); PG8_BAR; PG8_SCHED;
	v_mfma_f32_16x16x32_bf16 v[60:63], v[128:131], v[186:189], v[60:63]
	v_mfma_f32_16x16x32_bf16 v[56:59], v[136:139], v[186:189], v[56:59]
	v_mfma_f32_16x16x32_bf16 v[48:51], v[128:131], v[194:197], v[48:51]
	v_mfma_f32_16x16x32_bf16 v[44:47], v[136:139], v[194:197], v[44:47]
	v_mfma_f32_16x16x32_bf16 v[32:35], v[128:131], v[202:205], v[32:35]
	v_mfma_f32_16x16x32_bf16 v[28:31], v[136:139], v[202:205], v[28:31]
	v_mfma_f32_16x16x32_bf16 v[16:19], v[128:131], v[212:215], v[16:19]
	v_mfma_f32_16x16x32_bf16 v[12:15], v[136:139], v[212:215], v[12:15]
	v_mfma_f32_16x16x32_bf16 v[60:63], v[132:135], v[190:193], v[60:63]
	v_mfma_f32_16x16x32_bf16 v[56:59], v[140:143], v[190:193], v[56:59]
	v_mfma_f32_16x16x32_bf16 v[48:51], v[132:135], v[198:201], v[48:51]
	v_mfma_f32_16x16x32_bf16 v[44:47], v[140:143], v[198:201], v[44:47]
	v_mfma_f32_16x16x32_bf16 v[32:35], v[132:135], v[206:209], v[32:35]
	v_mfma_f32_16x16x32_bf16 v[28:31], v[140:143], v[206:209], v[28:31]
	v_mfma_f32_16x16x32_bf16 v[16:19], v[132:135], v[216:219], v[16:19]
	v_mfma_f32_16x16x32_bf16 v[12:15], v[140:143], v[216:219], v[12:15]
	v_mfma_f32_16x16x32_bf16 v[52:55], v[156:159], v[186:189], v[52:55]
	v_mfma_f32_16x16x32_bf16 v[40:43], v[170:173], v[186:189], v[40:43]
	v_mfma_f32_16x16x32_bf16 v[36:39], v[156:159], v[194:197], v[36:39]
	v_mfma_f32_16x16x32_bf16 v[24:27], v[170:173], v[194:197], v[24:27]
	v_mfma_f32_16x16x32_bf16 v[20:23], v[156:159], v[202:205], v[20:23]
	v_mfma_f32_16x16x32_bf16 v[8:11], v[170:173], v[202:205], v[8:11]
	v_mfma_f32_16x16x32_bf16 v[4:7], v[156:159], v[212:215], v[4:7]
	v_mfma_f32_16x16x32_bf16 v[0:3], v[170:173], v[212:215], v[0:3]
	v_mfma_f32_16x16x32_bf16 v[52:55], v[166:169], v[190:193], v[52:55]
	v_mfma_f32_16x16x32_bf16 v[40:43], v[182:185], v[190:193], v[40:43]
	v_mfma_f32_16x16x32_bf16 v[36:39], v[166:169], v[198:201], v[36:39]
	v_mfma_f32_16x16x32_bf16 v[24:27], v[182:185], v[198:201], v[24:27]
	v_mfma_f32_16x16x32_bf16 v[20:23], v[166:169], v[206:209], v[20:23]
	v_mfma_f32_16x16x32_bf16 v[8:11], v[182:185], v[206:209], v[8:11]
	v_mfma_f32_16x16x32_bf16 v[4:7], v[166:169], v[216:219], v[4:7]
	v_mfma_f32_16x16x32_bf16 v[0:3], v[182:185], v[216:219], v[0:3]
	s_barrier
	s_add_i32 s60, 0, 0x18000
	s_add_i32 s61, 0, 0x1c000
	v_add_u32_e32 v140, s60, v161
	v_add_u32_e32 v177, s61, v161
	ds_read_b128 v[128:131], v140
	ds_read_b128 v[132:135], v140 offset:1024
	ds_read_b128 v[136:139], v140 offset:2048
	ds_read_b128 v[140:143], v140 offset:3072
	ds_read_b128 v[156:159], v177
	ds_read_b128 v[166:169], v177 offset:1024
	ds_read_b128 v[170:173], v177 offset:2048
	ds_read_b128 v[182:185], v177 offset:3072
	s_add_u32 s20, s50, 0x40000
	s_addc_u32 s21, s51, 0
	s_mov_b32 m0, s67
	v_lshl_add_u64 v[226:227], s[20:21], 0, v[146:147]
	ds_read_b128 v[186:189], v165 offset:32768
	ds_read_b128 v[190:193], v165 offset:33792
	ds_read_b128 v[194:197], v165 offset:34816
	ds_read_b128 v[198:201], v165 offset:35840
	ds_read_b128 v[202:205], v165 offset:36864
	ds_read_b128 v[206:209], v165 offset:37888
	ds_read_b128 v[212:215], v165 offset:38912
	ds_read_b128 v[216:219], v165 offset:39936
	global_load_lds_dwordx4 v[226:227], off
	v_lshl_add_u64 v[226:227], s[20:21], 0, v[144:145]
	s_mov_b32 m0, s68
	s_nop 0
	global_load_lds_dwordx4 v[226:227], off
	s_waitcnt vmcnt(8)
	s_waitcnt lgkmcnt(0)
	s_barrier
	v_mfma_f32_16x16x32_bf16 v[124:127], v[128:131], v[186:189], v[124:127]
	v_mfma_f32_16x16x32_bf16 v[120:123], v[136:139], v[186:189], v[120:123]
	v_mfma_f32_16x16x32_bf16 v[112:115], v[128:131], v[194:197], v[112:115]
	v_mfma_f32_16x16x32_bf16 v[108:111], v[136:139], v[194:197], v[108:111]
	v_mfma_f32_16x16x32_bf16 v[96:99], v[128:131], v[202:205], v[96:99]
	v_mfma_f32_16x16x32_bf16 v[92:95], v[136:139], v[202:205], v[92:95]
	v_mfma_f32_16x16x32_bf16 v[80:83], v[128:131], v[212:215], v[80:83]
	v_mfma_f32_16x16x32_bf16 v[76:79], v[136:139], v[212:215], v[76:79]
	v_mfma_f32_16x16x32_bf16 v[124:127], v[132:135], v[190:193], v[124:127]
	v_mfma_f32_16x16x32_bf16 v[120:123], v[140:143], v[190:193], v[120:123]
	v_mfma_f32_16x16x32_bf16 v[112:115], v[132:135], v[198:201], v[112:115]
	v_mfma_f32_16x16x32_bf16 v[108:111], v[140:143], v[198:201], v[108:111]
	v_mfma_f32_16x16x32_bf16 v[96:99], v[132:135], v[206:209], v[96:99]
	v_mfma_f32_16x16x32_bf16 v[92:95], v[140:143], v[206:209], v[92:95]
	v_mfma_f32_16x16x32_bf16 v[80:83], v[132:135], v[216:219], v[80:83]
	v_mfma_f32_16x16x32_bf16 v[76:79], v[140:143], v[216:219], v[76:79]
	v_mfma_f32_16x16x32_bf16 v[116:119], v[156:159], v[186:189], v[116:119]
	v_mfma_f32_16x16x32_bf16 v[104:107], v[170:173], v[186:189], v[104:107]
	v_mfma_f32_16x16x32_bf16 v[100:103], v[156:159], v[194:197], v[100:103]
	v_mfma_f32_16x16x32_bf16 v[88:91], v[170:173], v[194:197], v[88:91]
	v_mfma_f32_16x16x32_bf16 v[84:87], v[156:159], v[202:205], v[84:87]
	v_mfma_f32_16x16x32_bf16 v[72:75], v[170:173], v[202:205], v[72:75]
	v_mfma_f32_16x16x32_bf16 v[68:71], v[156:159], v[212:215], v[68:71]
	v_mfma_f32_16x16x32_bf16 v[64:67], v[170:173], v[212:215], v[64:67]
	v_mfma_f32_16x16x32_bf16 v[116:119], v[166:169], v[190:193], v[116:119]
	v_mfma_f32_16x16x32_bf16 v[104:107], v[182:185], v[190:193], v[104:107]
	v_mfma_f32_16x16x32_bf16 v[100:103], v[166:169], v[198:201], v[100:103]
	v_mfma_f32_16x16x32_bf16 v[88:91], v[182:185], v[198:201], v[88:91]
	v_mfma_f32_16x16x32_bf16 v[84:87], v[166:169], v[206:209], v[84:87]
	v_mfma_f32_16x16x32_bf16 v[72:75], v[182:185], v[206:209], v[72:75]
	v_mfma_f32_16x16x32_bf16 v[68:71], v[166:169], v[216:219], v[68:71]
	v_mfma_f32_16x16x32_bf16 v[64:67], v[182:185], v[216:219], v[64:67]
	s_barrier
; #define PG8_STAGE(bufoff, gbase, voff) do { _Pragma("unroll") for (int _i = 0; _i < 2; ++_i) \
;         __builtin_amdgcn_global_load_lds((const unsigned*)((const char*)(gbase) + (voff)[_i]), (PG8_LAS unsigned*)(lds + (bufoff) + ldsw + _i * 8192), 16, 0, 0); } while (0)
; #define PG8_LDA(dst, b, h) do { _Pragma("unroll") for (int m = 0; m < 4; ++m) _Pragma("unroll") for (int k = 0; k < 2; ++k) dst[m][k] = *(const PG8_LAS bf16x8*)(lds + PG8_SA(b, h) + aoff + m * 2048 + k * 1024); } while (0)
; #define PG8_MMA(ai, bj, At, Bt) do { __builtin_amdgcn_s_setprio(1); _Pragma("unroll") for (int m = 0; m < 4; ++m) _Pragma("unroll") for (int n = 0; n < 2; ++n) _Pragma("unroll") for (int k = 0; k < 2; ++k) \
;         acc[ai][bj][m][n] = __builtin_amdgcn_mfma_f32_16x16x32_bf16(Bt[n][k], At[m][k], acc[ai][bj][m][n], 0, 0, 0); __builtin_amdgcn_s_setprio(0); } while (0)
; #define PG8_WAIT_V(n) asm volatile("s_waitcnt vmcnt(" #n ")" ::: "memory")
; #define PG8_WAIT_L(n) asm volatile("s_waitcnt lgkmcnt(" #n ")" ::: "memory")
; #define PG8_BAR __builtin_amdgcn_s_barrier()
; #define PG8_SCHED __builtin_amdgcn_sched_barrier(0)
; template <class Epi, class Sched, bool ALIGN_EPI = false, bool SP2 = false>
; __device__ __forceinline__ void gemm_phase(PG8_LAS unsigned char* lds, const Gemm g, const Sched& S, const Epi& E) {
;     ...
;         for (int t = 0; t < nt_u; t += 2) {
;             const bool last = (t == nt_u - 2);
;     ...
;             PG8_WAIT_V(8); PG8_WAIT_L(0); PG8_BAR; PG8_MMA(0, 0, At, B0); PG8_MMA(0, 1, At, B1); PG8_BAR; PG8_SCHED;
;             PG8_LDA(At, 1, 1); PG8_STAGE(PG8_SB(1, 0), b3, voffB); PG8_STAGE(PG8_SB(1, 1), b3 + hstep, voffB); PG8_STAGE(PG8_SA(1, 0), a3, voffA);
;             PG8_WAIT_V(8); PG8_WAIT_L(0); PG8_BAR; PG8_MMA(1, 0, At, B0); PG8_MMA(1, 1, At, B1); PG8_BAR; PG8_SCHED;
	s_add_i32 s20, s60, s3
	v_lshl_add_u64 v[174:175], v[174:175], 0, s[10:11]
	s_mov_b32 m0, s20
	ds_read_b128 v[186:189], v165 offset:49152
	ds_read_b128 v[190:193], v165 offset:50176
	ds_read_b128 v[194:197], v165 offset:51200
	ds_read_b128 v[198:201], v165 offset:52224
	ds_read_b128 v[202:205], v165 offset:53248
	ds_read_b128 v[206:209], v165 offset:54272
	ds_read_b128 v[212:215], v165 offset:55296
	ds_read_b128 v[216:219], v165 offset:56320
	global_load_lds_dwordx4 v[174:175], off
	s_add_i32 m0, s20, 0x2000
	s_add_u32 s20, s48, 0x40080
	v_lshl_add_u64 v[174:175], v[220:221], 0, s[10:11]
	s_addc_u32 s21, s49, 0
	s_add_i32 s48, s61, s3
	global_load_lds_dwordx4 v[174:175], off
	v_lshl_add_u64 v[174:175], s[20:21], 0, v[146:147]
	s_mov_b32 m0, s48
	s_nop 0
	global_load_lds_dwordx4 v[174:175], off
	v_lshl_add_u64 v[174:175], s[20:21], 0, v[144:145]
	s_add_i32 m0, s48, 0x2000
	s_nop 0
	global_load_lds_dwordx4 v[174:175], off
	v_lshl_add_u64 v[174:175], v[222:223], 0, s[10:11]
	s_mov_b32 m0, s71
	s_nop 0
	global_load_lds_dwordx4 v[174:175], off
	v_lshl_add_u64 v[174:175], v[224:225], 0, s[10:11]
	s_mov_b32 m0, s72
	s_nop 0
	global_load_lds_dwordx4 v[174:175], off
	s_waitcnt vmcnt(8)
	s_waitcnt lgkmcnt(0)
	s_barrier
	v_mfma_f32_16x16x32_bf16 v[60:63], v[128:131], v[186:189], v[60:63]
	v_mfma_f32_16x16x32_bf16 v[56:59], v[136:139], v[186:189], v[56:59]
	v_mfma_f32_16x16x32_bf16 v[48:51], v[128:131], v[194:197], v[48:51]
	v_mfma_f32_16x16x32_bf16 v[44:47], v[136:139], v[194:197], v[44:47]
	v_mfma_f32_16x16x32_bf16 v[32:35], v[128:131], v[202:205], v[32:35]
	v_mfma_f32_16x16x32_bf16 v[28:31], v[136:139], v[202:205], v[28:31]
	v_mfma_f32_16x16x32_bf16 v[16:19], v[128:131], v[212:215], v[16:19]
	v_mfma_f32_16x16x32_bf16 v[12:15], v[136:139], v[212:215], v[12:15]
	v_mfma_f32_16x16x32_bf16 v[60:63], v[132:135], v[190:193], v[60:63]
	v_mfma_f32_16x16x32_bf16 v[56:59], v[140:143], v[190:193], v[56:59]
	v_mfma_f32_16x16x32_bf16 v[48:51], v[132:135], v[198:201], v[48:51]
	v_mfma_f32_16x16x32_bf16 v[44:47], v[140:143], v[198:201], v[44:47]
	v_mfma_f32_16x16x32_bf16 v[32:35], v[132:135], v[206:209], v[32:35]
	v_mfma_f32_16x16x32_bf16 v[28:31], v[140:143], v[206:209], v[28:31]
	v_mfma_f32_16x16x32_bf16 v[16:19], v[132:135], v[216:219], v[16:19]
	v_mfma_f32_16x16x32_bf16 v[12:15], v[140:143], v[216:219], v[12:15]
	v_mfma_f32_16x16x32_bf16 v[52:55], v[156:159], v[186:189], v[52:55]
	v_mfma_f32_16x16x32_bf16 v[40:43], v[170:173], v[186:189], v[40:43]
	v_mfma_f32_16x16x32_bf16 v[36:39], v[156:159], v[194:197], v[36:39]
	v_mfma_f32_16x16x32_bf16 v[24:27], v[170:173], v[194:197], v[24:27]
	v_mfma_f32_16x16x32_bf16 v[20:23], v[156:159], v[202:205], v[20:23]
	v_mfma_f32_16x16x32_bf16 v[8:11], v[170:173], v[202:205], v[8:11]
	v_mfma_f32_16x16x32_bf16 v[4:7], v[156:159], v[212:215], v[4:7]
	v_mfma_f32_16x16x32_bf16 v[0:3], v[170:173], v[212:215], v[0:3]
	v_mfma_f32_16x16x32_bf16 v[52:55], v[166:169], v[190:193], v[52:55]
	v_mfma_f32_16x16x32_bf16 v[40:43], v[182:185], v[190:193], v[40:43]
	v_mfma_f32_16x16x32_bf16 v[36:39], v[166:169], v[198:201], v[36:39]
	v_mfma_f32_16x16x32_bf16 v[24:27], v[182:185], v[198:201], v[24:27]
	v_mfma_f32_16x16x32_bf16 v[20:23], v[166:169], v[206:209], v[20:23]
	v_mfma_f32_16x16x32_bf16 v[8:11], v[182:185], v[206:209], v[8:11]
	v_mfma_f32_16x16x32_bf16 v[4:7], v[166:169], v[216:219], v[4:7]
	v_mfma_f32_16x16x32_bf16 v[0:3], v[182:185], v[216:219], v[0:3]
	s_barrier
	s_add_i32 s79, s79, 2
	s_add_u32 s46, s46, 0x100
	s_addc_u32 s47, s47, 0
	s_add_u32 s45, s45, 0x100
	s_addc_u32 s78, s78, 0
	s_cmp_gt_u32 s79, 13
	s_cbranch_scc0 .LBB0_543
	s_and_b64 vcc, exec, s[28:29]
	s_cbranch_vccz .LBB0_546
	s_barrier

; #define PG8_STAGE(bufoff, gbase, voff) do { _Pragma("unroll") for (int _i = 0; _i < 2; ++_i) \
;         __builtin_amdgcn_global_load_lds((const unsigned*)((const char*)(gbase) + (voff)[_i]), (PG8_LAS unsigned*)(lds + (bufoff) + ldsw + _i * 8192), 16, 0, 0); } while (0)
; #define PG8_LDA(dst, b, h) do { _Pragma("unroll") for (int m = 0; m < 4; ++m) _Pragma("unroll") for (int k = 0; k < 2; ++k) dst[m][k] = *(const PG8_LAS bf16x8*)(lds + PG8_SA(b, h) + aoff + m * 2048 + k * 1024); } while (0)
; #define PG8_LDB(dst, b, h) do { _Pragma("unroll") for (int n = 0; n < 2; ++n) _Pragma("unroll") for (int k = 0; k < 2; ++k) dst[n][k] = *(const PG8_LAS bf16x8*)(lds + PG8_SB(b, h) + boff + n * 2048 + k * 1024); } while (0)
; #define PG8_MMA(ai, bj, At, Bt) do { __builtin_amdgcn_s_setprio(1); _Pragma("unroll") for (int m = 0; m < 4; ++m) _Pragma("unroll") for (int n = 0; n < 2; ++n) _Pragma("unroll") for (int k = 0; k < 2; ++k) \
;         acc[ai][bj][m][n] = __builtin_amdgcn_mfma_f32_16x16x32_bf16(Bt[n][k], At[m][k], acc[ai][bj][m][n], 0, 0, 0); __builtin_amdgcn_s_setprio(0); } while (0)
; #define PG8_WAIT_V(n) asm volatile("s_waitcnt vmcnt(" #n ")" ::: "memory")
; #define PG8_WAIT_L(n) asm volatile("s_waitcnt lgkmcnt(" #n ")" ::: "memory")
; #define PG8_BAR __builtin_amdgcn_s_barrier()
; #define PG8_SCHED __builtin_amdgcn_sched_barrier(0)
; template <class Epi, class Sched, bool ALIGN_EPI = false, bool SP2 = false>
; __device__ __forceinline__ void gemm_phase(PG8_LAS unsigned char* lds, const Gemm g, const Sched& S, const Epi& E) {
;     ...
;             const bool last = (t == nt_u - 2);
;             const char* a1 = cA + (size_t)(t + 1) * kstep;
;             const char* a2 = last ? nA : cA + (size_t)(t + 2) * kstep; const char* b2 = last ? nB : cB + (size_t)(t + 2) * kstep;
;             const char* a3 = a2 + kstep; const char* b3 = b2 + kstep;
;             if (last && has_next) S.a_ready(nxt);
;             if constexpr (SP2) {
;             PG8_LDB(B0, 0, 0); PG8_LDB(B1, 0, 1); PG8_SCHED; PG8_LDA(At, 0, 0); PG8_STAGE(PG8_SA(1, 1), a1 + hstep, voffA);
;             PG8_WAIT_V(8); PG8_WAIT_L(0); PG8_BAR; PG8_MMA(0, 0, At, B0); PG8_MMA(0, 1, At, B1); PG8_BAR; PG8_SCHED;
;             PG8_LDA(At, 0, 1); PG8_STAGE(PG8_SB(0, 0), b2, voffB); PG8_STAGE(PG8_SB(0, 1), b2 + hstep, voffB); PG8_STAGE(PG8_SA(0, 0), a2, voffA);
.LBB0_668:
	ds_read_b128 v[128:131], v207
	ds_read_b128 v[132:135], v207 offset:1024
	ds_read_b128 v[136:139], v207 offset:2048
	ds_read_b128 v[140:143], v207 offset:3072
	ds_read_b128 v[144:147], v208
	ds_read_b128 v[148:151], v208 offset:1024
	ds_read_b128 v[152:155], v208 offset:2048
	ds_read_b128 v[156:159], v208 offset:3072
	s_add_u32 s16, s0, 0xfffc0080
	s_addc_u32 s17, s1, -1
	s_cmp_eq_u32 s83, 12
	s_cselect_b32 s63, s12, s17
	s_cselect_b32 s62, s13, s16
	s_cselect_b32 s17, s45, s82
	s_cselect_b32 s16, s47, s81
	v_lshl_add_u64 v[196:197], s[0:1], 0, v[168:169]
	s_add_i32 m0, s66, 0xc000
	ds_read_b128 v[180:183], v209
	ds_read_b128 v[184:187], v209 offset:1024
	ds_read_b128 v[188:191], v209 offset:2048
	ds_read_b128 v[192:195], v209 offset:3072
	ds_read_b128 v[212:215], v209 offset:4096
	ds_read_b128 v[216:219], v209 offset:5120
	ds_read_b128 v[220:223], v209 offset:6144
	ds_read_b128 v[224:227], v209 offset:7168
	global_load_lds_dwordx4 v[196:197], off
	v_lshl_add_u64 v[196:197], s[0:1], 0, v[170:171]
	s_add_i32 m0, s66, 0xe000
	s_nop 0
	global_load_lds_dwordx4 v[196:197], off
	s_waitcnt vmcnt(8)
	s_waitcnt lgkmcnt(0)
	s_barrier
	v_mfma_f32_16x16x32_bf16 v[124:127], v[128:131], v[180:183], v[124:127]
	v_mfma_f32_16x16x32_bf16 v[60:63], v[136:139], v[180:183], v[60:63]
	v_mfma_f32_16x16x32_bf16 v[116:119], v[128:131], v[188:191], v[116:119]
	v_mfma_f32_16x16x32_bf16 v[52:55], v[136:139], v[188:191], v[52:55]
	v_mfma_f32_16x16x32_bf16 v[108:111], v[128:131], v[212:215], v[108:111]
	v_mfma_f32_16x16x32_bf16 v[44:47], v[136:139], v[212:215], v[44:47]
	v_mfma_f32_16x16x32_bf16 v[104:107], v[128:131], v[220:223], v[104:107]
	v_mfma_f32_16x16x32_bf16 v[40:43], v[136:139], v[220:223], v[40:43]
	v_mfma_f32_16x16x32_bf16 v[124:127], v[132:135], v[184:187], v[124:127]
	v_mfma_f32_16x16x32_bf16 v[60:63], v[140:143], v[184:187], v[60:63]
	v_mfma_f32_16x16x32_bf16 v[116:119], v[132:135], v[192:195], v[116:119]
	v_mfma_f32_16x16x32_bf16 v[52:55], v[140:143], v[192:195], v[52:55]
	v_mfma_f32_16x16x32_bf16 v[108:111], v[132:135], v[216:219], v[108:111]
	v_mfma_f32_16x16x32_bf16 v[44:47], v[140:143], v[216:219], v[44:47]
	v_mfma_f32_16x16x32_bf16 v[104:107], v[132:135], v[224:227], v[104:107]
	v_mfma_f32_16x16x32_bf16 v[40:43], v[140:143], v[224:227], v[40:43]
	v_mfma_f32_16x16x32_bf16 v[120:123], v[144:147], v[180:183], v[120:123]
	v_mfma_f32_16x16x32_bf16 v[56:59], v[152:155], v[180:183], v[56:59]
	v_mfma_f32_16x16x32_bf16 v[112:115], v[144:147], v[188:191], v[112:115]
	v_mfma_f32_16x16x32_bf16 v[48:51], v[152:155], v[188:191], v[48:51]
	v_mfma_f32_16x16x32_bf16 v[100:103], v[144:147], v[212:215], v[100:103]
	v_mfma_f32_16x16x32_bf16 v[36:39], v[152:155], v[212:215], v[36:39]
	v_mfma_f32_16x16x32_bf16 v[96:99], v[144:147], v[220:223], v[96:99]
	v_mfma_f32_16x16x32_bf16 v[32:35], v[152:155], v[220:223], v[32:35]
	v_mfma_f32_16x16x32_bf16 v[120:123], v[148:151], v[184:187], v[120:123]
	v_mfma_f32_16x16x32_bf16 v[56:59], v[156:159], v[184:187], v[56:59]
	v_mfma_f32_16x16x32_bf16 v[112:115], v[148:151], v[192:195], v[112:115]
	v_mfma_f32_16x16x32_bf16 v[48:51], v[156:159], v[192:195], v[48:51]
	v_mfma_f32_16x16x32_bf16 v[100:103], v[148:151], v[216:219], v[100:103]
	v_mfma_f32_16x16x32_bf16 v[36:39], v[156:159], v[216:219], v[36:39]
	v_mfma_f32_16x16x32_bf16 v[96:99], v[148:151], v[224:227], v[96:99]
	v_mfma_f32_16x16x32_bf16 v[32:35], v[156:159], v[224:227], v[32:35]
	s_barrier
	s_add_i32 s20, s77, s3
	v_lshl_add_u64 v[196:197], s[16:17], 0, v[162:163]
	s_mov_b32 m0, s20
	ds_read_b128 v[180:183], v209 offset:16384
	ds_read_b128 v[184:187], v209 offset:17408
	ds_read_b128 v[188:191], v209 offset:18432
	ds_read_b128 v[192:195], v209 offset:19456
	ds_read_b128 v[212:215], v209 offset:20480
	ds_read_b128 v[216:219], v209 offset:21504
	ds_read_b128 v[220:223], v209 offset:22528
	ds_read_b128 v[224:227], v209 offset:23552
	global_load_lds_dwordx4 v[196:197], off
	s_add_i32 m0, s20, 0x2000
	s_add_u32 s20, s16, 0x40000
	v_lshl_add_u64 v[228:229], s[16:17], 0, v[160:161]
	s_addc_u32 s21, s17, 0
	s_add_i32 s64, s78, s3
	global_load_lds_dwordx4 v[228:229], off
	v_lshl_add_u64 v[230:231], s[20:21], 0, v[162:163]
	s_mov_b32 m0, s64
	v_lshl_add_u64 v[232:233], s[62:63], 0, v[160:161]
	global_load_lds_dwordx4 v[230:231], off
	v_lshl_add_u64 v[230:231], s[20:21], 0, v[160:161]
	s_add_i32 m0, s64, 0x2000
	s_nop 0
	global_load_lds_dwordx4 v[230:231], off
	v_lshl_add_u64 v[230:231], s[62:63], 0, v[162:163]
	s_mov_b32 m0, s66
	s_nop 0
	global_load_lds_dwordx4 v[230:231], off
	s_mov_b32 m0, s67
	s_nop 0
	global_load_lds_dwordx4 v[232:233], off
	s_waitcnt vmcnt(8)
	s_waitcnt lgkmcnt(0)
	s_barrier
; #define PG8_STAGE(bufoff, gbase, voff) do { _Pragma("unroll") for (int _i = 0; _i < 2; ++_i) \
;         __builtin_amdgcn_global_load_lds((const unsigned*)((const char*)(gbase) + (voff)[_i]), (PG8_LAS unsigned*)(lds + (bufoff) + ldsw + _i * 8192), 16, 0, 0); } while (0)
; #define PG8_LDA(dst, b, h) do { _Pragma("unroll") for (int m = 0; m < 4; ++m) _Pragma("unroll") for (int k = 0; k < 2; ++k) dst[m][k] = *(const PG8_LAS bf16x8*)(lds + PG8_SA(b, h) + aoff + m * 2048 + k * 1024); } while (0)
; #define PG8_LDB(dst, b, h) do { _Pragma("unroll") for (int n = 0; n < 2; ++n) _Pragma("unroll") for (int k = 0; k < 2; ++k) dst[n][k] = *(const PG8_LAS bf16x8*)(lds + PG8_SB(b, h) + boff + n * 2048 + k * 1024); } while (0)
; #define PG8_MMA(ai, bj, At, Bt) do { __builtin_amdgcn_s_setprio(1); _Pragma("unroll") for (int m = 0; m < 4; ++m) _Pragma("unroll") for (int n = 0; n < 2; ++n) _Pragma("unroll") for (int k = 0; k < 2; ++k) \
;         acc[ai][bj][m][n] = __builtin_amdgcn_mfma_f32_16x16x32_bf16(Bt[n][k], At[m][k], acc[ai][bj][m][n], 0, 0, 0); __builtin_amdgcn_s_setprio(0); } while (0)
; #define PG8_WAIT_V(n) asm volatile("s_waitcnt vmcnt(" #n ")" ::: "memory")
; #define PG8_WAIT_L(n) asm volatile("s_waitcnt lgkmcnt(" #n ")" ::: "memory")
; #define PG8_BAR __builtin_amdgcn_s_barrier()
; #define PG8_SCHED __builtin_amdgcn_sched_barrier(0)
; template <class Epi, class Sched, bool ALIGN_EPI = false, bool SP2 = false>
; __device__ __forceinline__ void gemm_phase(PG8_LAS unsigned char* lds, const Gemm g, const Sched& S, const Epi& E) {
;     ...
;             PG8_WAIT_V(8); PG8_WAIT_L(0); PG8_BAR; PG8_MMA(0, 0, At, B0); PG8_MMA(0, 1, At, B1); PG8_BAR; PG8_SCHED;
;             PG8_LDA(At, 0, 1); PG8_STAGE(PG8_SB(0, 0), b2, voffB); PG8_STAGE(PG8_SB(0, 1), b2 + hstep, voffB); PG8_STAGE(PG8_SA(0, 0), a2, voffA);
;             PG8_WAIT_V(8); PG8_WAIT_L(0); PG8_BAR; PG8_MMA(1, 0, At, B0); PG8_MMA(1, 1, At, B1); PG8_BAR; PG8_SCHED;
;             PG8_LDB(B0, 1, 0); PG8_LDB(B1, 1, 1); PG8_SCHED; PG8_LDA(At, 1, 0); PG8_STAGE(PG8_SA(0, 1), a2 + hstep, voffA);
;             PG8_WAIT_V(8); PG8_WAIT_L(0); PG8_BAR; PG8_MMA(0, 0, At, B0); PG8_MMA(0, 1, At, B1); PG8_BAR; PG8_SCHED;
	v_mfma_f32_16x16x32_bf16 v[92:95], v[128:131], v[180:183], v[92:95]
	v_mfma_f32_16x16x32_bf16 v[28:31], v[136:139], v[180:183], v[28:31]
	v_mfma_f32_16x16x32_bf16 v[84:87], v[128:131], v[188:191], v[84:87]
	v_mfma_f32_16x16x32_bf16 v[20:23], v[136:139], v[188:191], v[20:23]
	v_mfma_f32_16x16x32_bf16 v[76:79], v[128:131], v[212:215], v[76:79]
	v_mfma_f32_16x16x32_bf16 v[12:15], v[136:139], v[212:215], v[12:15]
	v_mfma_f32_16x16x32_bf16 v[72:75], v[128:131], v[220:223], v[72:75]
	v_mfma_f32_16x16x32_bf16 v[8:11], v[136:139], v[220:223], v[8:11]
	v_mfma_f32_16x16x32_bf16 v[92:95], v[132:135], v[184:187], v[92:95]
	v_mfma_f32_16x16x32_bf16 v[28:31], v[140:143], v[184:187], v[28:31]
	v_mfma_f32_16x16x32_bf16 v[84:87], v[132:135], v[192:195], v[84:87]
	v_mfma_f32_16x16x32_bf16 v[20:23], v[140:143], v[192:195], v[20:23]
	v_mfma_f32_16x16x32_bf16 v[76:79], v[132:135], v[216:219], v[76:79]
	v_mfma_f32_16x16x32_bf16 v[12:15], v[140:143], v[216:219], v[12:15]
	v_mfma_f32_16x16x32_bf16 v[72:75], v[132:135], v[224:227], v[72:75]
	v_mfma_f32_16x16x32_bf16 v[8:11], v[140:143], v[224:227], v[8:11]
	v_mfma_f32_16x16x32_bf16 v[88:91], v[144:147], v[180:183], v[88:91]
	v_mfma_f32_16x16x32_bf16 v[24:27], v[152:155], v[180:183], v[24:27]
	v_mfma_f32_16x16x32_bf16 v[80:83], v[144:147], v[188:191], v[80:83]
	v_mfma_f32_16x16x32_bf16 v[16:19], v[152:155], v[188:191], v[16:19]
	v_mfma_f32_16x16x32_bf16 v[68:71], v[144:147], v[212:215], v[68:71]
	v_mfma_f32_16x16x32_bf16 v[4:7], v[152:155], v[212:215], v[4:7]
	v_mfma_f32_16x16x32_bf16 v[64:67], v[144:147], v[220:223], v[64:67]
	v_mfma_f32_16x16x32_bf16 v[0:3], v[152:155], v[220:223], v[0:3]
	v_mfma_f32_16x16x32_bf16 v[88:91], v[148:151], v[184:187], v[88:91]
	v_mfma_f32_16x16x32_bf16 v[24:27], v[156:159], v[184:187], v[24:27]
	v_mfma_f32_16x16x32_bf16 v[80:83], v[148:151], v[192:195], v[80:83]
	v_mfma_f32_16x16x32_bf16 v[16:19], v[156:159], v[192:195], v[16:19]
	v_mfma_f32_16x16x32_bf16 v[68:71], v[148:151], v[216:219], v[68:71]
	v_mfma_f32_16x16x32_bf16 v[4:7], v[156:159], v[216:219], v[4:7]
	v_mfma_f32_16x16x32_bf16 v[64:67], v[148:151], v[224:227], v[64:67]
	v_mfma_f32_16x16x32_bf16 v[0:3], v[156:159], v[224:227], v[0:3]
	s_barrier
	s_add_i32 s64, 0, 0x18000
	s_add_i32 s65, 0, 0x1c000
	v_add_u32_e32 v140, s64, v177
	v_add_u32_e32 v156, s65, v177
	ds_read_b128 v[128:131], v140
	ds_read_b128 v[132:135], v140 offset:1024
	ds_read_b128 v[136:139], v140 offset:2048
	ds_read_b128 v[140:143], v140 offset:3072
	ds_read_b128 v[144:147], v156
	ds_read_b128 v[148:151], v156 offset:1024
	ds_read_b128 v[152:155], v156 offset:2048
	ds_read_b128 v[156:159], v156 offset:3072
	s_add_u32 s20, s62, 0x40000
	s_addc_u32 s21, s63, 0
	s_mov_b32 m0, s68
	v_lshl_add_u64 v[234:235], s[20:21], 0, v[162:163]
	ds_read_b128 v[180:183], v209 offset:32768
	ds_read_b128 v[184:187], v209 offset:33792
	ds_read_b128 v[188:191], v209 offset:34816
	ds_read_b128 v[192:195], v209 offset:35840
	ds_read_b128 v[212:215], v209 offset:36864
	ds_read_b128 v[216:219], v209 offset:37888
	ds_read_b128 v[220:223], v209 offset:38912
	ds_read_b128 v[224:227], v209 offset:39936
	global_load_lds_dwordx4 v[234:235], off
	v_lshl_add_u64 v[234:235], s[20:21], 0, v[160:161]
	s_mov_b32 m0, s69
	s_nop 0
	global_load_lds_dwordx4 v[234:235], off
	s_waitcnt vmcnt(8)
	s_waitcnt lgkmcnt(0)
	s_barrier
	v_mfma_f32_16x16x32_bf16 v[124:127], v[128:131], v[180:183], v[124:127]
	v_mfma_f32_16x16x32_bf16 v[60:63], v[136:139], v[180:183], v[60:63]
	v_mfma_f32_16x16x32_bf16 v[116:119], v[128:131], v[188:191], v[116:119]
	v_mfma_f32_16x16x32_bf16 v[52:55], v[136:139], v[188:191], v[52:55]
	v_mfma_f32_16x16x32_bf16 v[108:111], v[128:131], v[212:215], v[108:111]
	v_mfma_f32_16x16x32_bf16 v[44:47], v[136:139], v[212:215], v[44:47]
	v_mfma_f32_16x16x32_bf16 v[104:107], v[128:131], v[220:223], v[104:107]
	v_mfma_f32_16x16x32_bf16 v[40:43], v[136:139], v[220:223], v[40:43]
	v_mfma_f32_16x16x32_bf16 v[124:127], v[132:135], v[184:187], v[124:127]
	v_mfma_f32_16x16x32_bf16 v[60:63], v[140:143], v[184:187], v[60:63]
	v_mfma_f32_16x16x32_bf16 v[116:119], v[132:135], v[192:195], v[116:119]
	v_mfma_f32_16x16x32_bf16 v[52:55], v[140:143], v[192:195], v[52:55]
	v_mfma_f32_16x16x32_bf16 v[108:111], v[132:135], v[216:219], v[108:111]
	v_mfma_f32_16x16x32_bf16 v[44:47], v[140:143], v[216:219], v[44:47]
	v_mfma_f32_16x16x32_bf16 v[104:107], v[132:135], v[224:227], v[104:107]
	v_mfma_f32_16x16x32_bf16 v[40:43], v[140:143], v[224:227], v[40:43]
	v_mfma_f32_16x16x32_bf16 v[120:123], v[144:147], v[180:183], v[120:123]
	v_mfma_f32_16x16x32_bf16 v[56:59], v[152:155], v[180:183], v[56:59]
	v_mfma_f32_16x16x32_bf16 v[112:115], v[144:147], v[188:191], v[112:115]
	v_mfma_f32_16x16x32_bf16 v[48:51], v[152:155], v[188:191], v[48:51]
	v_mfma_f32_16x16x32_bf16 v[100:103], v[144:147], v[212:215], v[100:103]
	v_mfma_f32_16x16x32_bf16 v[36:39], v[152:155], v[212:215], v[36:39]
	v_mfma_f32_16x16x32_bf16 v[96:99], v[144:147], v[220:223], v[96:99]
	v_mfma_f32_16x16x32_bf16 v[32:35], v[152:155], v[220:223], v[32:35]
	v_mfma_f32_16x16x32_bf16 v[120:123], v[148:151], v[184:187], v[120:123]
	v_mfma_f32_16x16x32_bf16 v[56:59], v[156:159], v[184:187], v[56:59]
	v_mfma_f32_16x16x32_bf16 v[112:115], v[148:151], v[192:195], v[112:115]
	v_mfma_f32_16x16x32_bf16 v[48:51], v[156:159], v[192:195], v[48:51]
	v_mfma_f32_16x16x32_bf16 v[100:103], v[148:151], v[216:219], v[100:103]
	v_mfma_f32_16x16x32_bf16 v[36:39], v[156:159], v[216:219], v[36:39]
	v_mfma_f32_16x16x32_bf16 v[96:99], v[148:151], v[224:227], v[96:99]
	v_mfma_f32_16x16x32_bf16 v[32:35], v[156:159], v[224:227], v[32:35]
	s_barrier
; #define PG8_STAGE(bufoff, gbase, voff) do { _Pragma("unroll") for (int _i = 0; _i < 2; ++_i) \
;         __builtin_amdgcn_global_load_lds((const unsigned*)((const char*)(gbase) + (voff)[_i]), (PG8_LAS unsigned*)(lds + (bufoff) + ldsw + _i * 8192), 16, 0, 0); } while (0)
; #define PG8_LDA(dst, b, h) do { _Pragma("unroll") for (int m = 0; m < 4; ++m) _Pragma("unroll") for (int k = 0; k < 2; ++k) dst[m][k] = *(const PG8_LAS bf16x8*)(lds + PG8_SA(b, h) + aoff + m * 2048 + k * 1024); } while (0)
; #define PG8_MMA(ai, bj, At, Bt) do { __builtin_amdgcn_s_setprio(1); _Pragma("unroll") for (int m = 0; m < 4; ++m) _Pragma("unroll") for (int n = 0; n < 2; ++n) _Pragma("unroll") for (int k = 0; k < 2; ++k) \
;         acc[ai][bj][m][n] = __builtin_amdgcn_mfma_f32_16x16x32_bf16(Bt[n][k], At[m][k], acc[ai][bj][m][n], 0, 0, 0); __builtin_amdgcn_s_setprio(0); } while (0)
; #define PG8_WAIT_V(n) asm volatile("s_waitcnt vmcnt(" #n ")" ::: "memory")
; #define PG8_WAIT_L(n) asm volatile("s_waitcnt lgkmcnt(" #n ")" ::: "memory")
; #define PG8_BAR __builtin_amdgcn_s_barrier()
; #define PG8_SCHED __builtin_amdgcn_sched_barrier(0)
; template <class Epi, class Sched, bool ALIGN_EPI = false, bool SP2 = false>
; __device__ __forceinline__ void gemm_phase(PG8_LAS unsigned char* lds, const Gemm g, const Sched& S, const Epi& E) {
;     ...
;         for (int t = 0; t < nt_u; t += 2) {
;             const bool last = (t == nt_u - 2);
;     ...
;             PG8_WAIT_V(8); PG8_WAIT_L(0); PG8_BAR; PG8_MMA(0, 0, At, B0); PG8_MMA(0, 1, At, B1); PG8_BAR; PG8_SCHED;
;             PG8_LDA(At, 1, 1); PG8_STAGE(PG8_SB(1, 0), b3, voffB); PG8_STAGE(PG8_SB(1, 1), b3 + hstep, voffB); PG8_STAGE(PG8_SA(1, 0), a3, voffA);
;             PG8_WAIT_V(8); PG8_WAIT_L(0); PG8_BAR; PG8_MMA(1, 0, At, B0); PG8_MMA(1, 1, At, B1); PG8_BAR; PG8_SCHED;
	s_add_i32 s20, s64, s3
	v_lshl_add_u64 v[196:197], v[196:197], 0, s[30:31]
	s_mov_b32 m0, s20
	ds_read_b128 v[180:183], v209 offset:49152
	ds_read_b128 v[184:187], v209 offset:50176
	ds_read_b128 v[188:191], v209 offset:51200
	ds_read_b128 v[192:195], v209 offset:52224
	ds_read_b128 v[212:215], v209 offset:53248
	ds_read_b128 v[216:219], v209 offset:54272
	ds_read_b128 v[220:223], v209 offset:55296
	ds_read_b128 v[224:227], v209 offset:56320
	global_load_lds_dwordx4 v[196:197], off
	s_add_i32 m0, s20, 0x2000
	s_add_u32 s16, s16, 0x40080
	v_lshl_add_u64 v[196:197], v[228:229], 0, s[30:31]
	s_addc_u32 s17, s17, 0
	s_add_i32 s20, s65, s3
	global_load_lds_dwordx4 v[196:197], off
	v_lshl_add_u64 v[196:197], s[16:17], 0, v[162:163]
	s_mov_b32 m0, s20
	s_nop 0
	global_load_lds_dwordx4 v[196:197], off
	v_lshl_add_u64 v[196:197], s[16:17], 0, v[160:161]
	s_add_i32 m0, s20, 0x2000
	s_nop 0
	global_load_lds_dwordx4 v[196:197], off
	v_lshl_add_u64 v[196:197], v[230:231], 0, s[30:31]
	s_mov_b32 m0, s71
	s_nop 0
	global_load_lds_dwordx4 v[196:197], off
	v_lshl_add_u64 v[196:197], v[232:233], 0, s[30:31]
	s_mov_b32 m0, s72
	s_nop 0
	global_load_lds_dwordx4 v[196:197], off
	s_waitcnt vmcnt(8)
	s_waitcnt lgkmcnt(0)
	s_barrier
	v_mfma_f32_16x16x32_bf16 v[92:95], v[128:131], v[180:183], v[92:95]
	v_mfma_f32_16x16x32_bf16 v[28:31], v[136:139], v[180:183], v[28:31]
	v_mfma_f32_16x16x32_bf16 v[84:87], v[128:131], v[188:191], v[84:87]
	v_mfma_f32_16x16x32_bf16 v[20:23], v[136:139], v[188:191], v[20:23]
	v_mfma_f32_16x16x32_bf16 v[76:79], v[128:131], v[212:215], v[76:79]
	v_mfma_f32_16x16x32_bf16 v[12:15], v[136:139], v[212:215], v[12:15]
	v_mfma_f32_16x16x32_bf16 v[72:75], v[128:131], v[220:223], v[72:75]
	v_mfma_f32_16x16x32_bf16 v[8:11], v[136:139], v[220:223], v[8:11]
	v_mfma_f32_16x16x32_bf16 v[92:95], v[132:135], v[184:187], v[92:95]
	v_mfma_f32_16x16x32_bf16 v[28:31], v[140:143], v[184:187], v[28:31]
	v_mfma_f32_16x16x32_bf16 v[84:87], v[132:135], v[192:195], v[84:87]
	v_mfma_f32_16x16x32_bf16 v[20:23], v[140:143], v[192:195], v[20:23]
	v_mfma_f32_16x16x32_bf16 v[76:79], v[132:135], v[216:219], v[76:79]
	v_mfma_f32_16x16x32_bf16 v[12:15], v[140:143], v[216:219], v[12:15]
	v_mfma_f32_16x16x32_bf16 v[72:75], v[132:135], v[224:227], v[72:75]
	v_mfma_f32_16x16x32_bf16 v[8:11], v[140:143], v[224:227], v[8:11]
	v_mfma_f32_16x16x32_bf16 v[88:91], v[144:147], v[180:183], v[88:91]
	v_mfma_f32_16x16x32_bf16 v[24:27], v[152:155], v[180:183], v[24:27]
	v_mfma_f32_16x16x32_bf16 v[80:83], v[144:147], v[188:191], v[80:83]
	v_mfma_f32_16x16x32_bf16 v[16:19], v[152:155], v[188:191], v[16:19]
	v_mfma_f32_16x16x32_bf16 v[68:71], v[144:147], v[212:215], v[68:71]
	v_mfma_f32_16x16x32_bf16 v[4:7], v[152:155], v[212:215], v[4:7]
	v_mfma_f32_16x16x32_bf16 v[64:67], v[144:147], v[220:223], v[64:67]
	v_mfma_f32_16x16x32_bf16 v[0:3], v[152:155], v[220:223], v[0:3]
	v_mfma_f32_16x16x32_bf16 v[88:91], v[148:151], v[184:187], v[88:91]
	v_mfma_f32_16x16x32_bf16 v[24:27], v[156:159], v[184:187], v[24:27]
	v_mfma_f32_16x16x32_bf16 v[80:83], v[148:151], v[192:195], v[80:83]
	v_mfma_f32_16x16x32_bf16 v[16:19], v[156:159], v[192:195], v[16:19]
	v_mfma_f32_16x16x32_bf16 v[68:71], v[148:151], v[216:219], v[68:71]
	v_mfma_f32_16x16x32_bf16 v[4:7], v[156:159], v[216:219], v[4:7]
	v_mfma_f32_16x16x32_bf16 v[64:67], v[148:151], v[224:227], v[64:67]
	v_mfma_f32_16x16x32_bf16 v[0:3], v[156:159], v[224:227], v[0:3]
	s_barrier
	s_add_i32 s83, s83, 2
	s_add_u32 s0, s0, 0x100
	s_addc_u32 s1, s1, 0
	s_add_u32 s81, s81, 0x100
	s_addc_u32 s82, s82, 0
	s_cmp_gt_u32 s83, 13
	s_cbranch_scc0 .LBB0_668
	s_and_b64 vcc, exec, s[36:37]
	s_cbranch_vccnz .LBB0_680
	s_and_saveexec_b64 s[0:1], s[6:7]
	s_cbranch_execnz .LBB0_681

; #define PG8_STAGE(bufoff, gbase, voff) do { _Pragma("unroll") for (int _i = 0; _i < 2; ++_i) \
;         __builtin_amdgcn_global_load_lds((const unsigned*)((const char*)(gbase) + (voff)[_i]), (PG8_LAS unsigned*)(lds + (bufoff) + ldsw + _i * 8192), 16, 0, 0); } while (0)
; #define PG8_LDA(dst, b, h) do { _Pragma("unroll") for (int m = 0; m < 4; ++m) _Pragma("unroll") for (int k = 0; k < 2; ++k) dst[m][k] = *(const PG8_LAS bf16x8*)(lds + PG8_SA(b, h) + aoff + m * 2048 + k * 1024); } while (0)
; #define PG8_LDB(dst, b, h) do { _Pragma("unroll") for (int n = 0; n < 2; ++n) _Pragma("unroll") for (int k = 0; k < 2; ++k) dst[n][k] = *(const PG8_LAS bf16x8*)(lds + PG8_SB(b, h) + boff + n * 2048 + k * 1024); } while (0)
; #define PG8_MMA(ai, bj, At, Bt) do { __builtin_amdgcn_s_setprio(1); _Pragma("unroll") for (int m = 0; m < 4; ++m) _Pragma("unroll") for (int n = 0; n < 2; ++n) _Pragma("unroll") for (int k = 0; k < 2; ++k) \
;         acc[ai][bj][m][n] = __builtin_amdgcn_mfma_f32_16x16x32_bf16(Bt[n][k], At[m][k], acc[ai][bj][m][n], 0, 0, 0); __builtin_amdgcn_s_setprio(0); } while (0)
; #define PG8_WAIT_V(n) asm volatile("s_waitcnt vmcnt(" #n ")" ::: "memory")
; #define PG8_WAIT_L(n) asm volatile("s_waitcnt lgkmcnt(" #n ")" ::: "memory")
; #define PG8_BAR __builtin_amdgcn_s_barrier()
; #define PG8_SCHED __builtin_amdgcn_sched_barrier(0)
; template <class Epi, class Sched, bool ALIGN_EPI = false, bool SP2 = false>
; __device__ __forceinline__ void gemm_phase(PG8_LAS unsigned char* lds, const Gemm g, const Sched& S, const Epi& E) {
;     ...
;             const bool last = (t == nt_u - 2);
;             const char* a1 = cA + (size_t)(t + 1) * kstep;
;             const char* a2 = last ? nA : cA + (size_t)(t + 2) * kstep; const char* b2 = last ? nB : cB + (size_t)(t + 2) * kstep;
;             const char* a3 = a2 + kstep; const char* b3 = b2 + kstep;
;             if (last && has_next) S.a_ready(nxt);
;             if constexpr (SP2) {
;             PG8_LDB(B0, 0, 0); PG8_LDB(B1, 0, 1); PG8_SCHED; PG8_LDA(At, 0, 0); PG8_STAGE(PG8_SA(1, 1), a1 + hstep, voffA);
;             PG8_WAIT_V(8); PG8_WAIT_L(0); PG8_BAR; PG8_MMA(0, 0, At, B0); PG8_MMA(0, 1, At, B1); PG8_BAR; PG8_SCHED;
;             PG8_LDA(At, 0, 1); PG8_STAGE(PG8_SB(0, 0), b2, voffB); PG8_STAGE(PG8_SB(0, 1), b2 + hstep, voffB); PG8_STAGE(PG8_SA(0, 0), a2, voffA);
.LBB0_822:
	ds_read_b128 v[64:67], v161
	ds_read_b128 v[108:111], v161 offset:1024
	ds_read_b128 v[112:115], v161 offset:2048
	ds_read_b128 v[120:123], v161 offset:3072
	ds_read_b128 v[154:157], v162
	ds_read_b128 v[164:167], v162 offset:1024
	ds_read_b128 v[168:171], v162 offset:2048
	ds_read_b128 v[172:175], v162 offset:3072
	s_add_i32 s69, s36, 2
	s_add_u32 s30, s28, 0x100
	s_addc_u32 s31, s29, 0
	s_cmp_eq_u32 s12, s36
	s_cselect_b32 s36, s26, s13
	s_cselect_b32 s39, s25, s31
	s_cselect_b32 s38, s24, s30
	s_cselect_b32 s37, s27, s23
	v_lshl_add_u64 v[210:211], s[28:29], 0, v[148:149]
	s_add_i32 m0, s41, 0xc000
	ds_read_b128 v[178:181], v163
	ds_read_b128 v[182:185], v163 offset:1024
	ds_read_b128 v[186:189], v163 offset:2048
	ds_read_b128 v[190:193], v163 offset:3072
	ds_read_b128 v[194:197], v163 offset:4096
	ds_read_b128 v[198:201], v163 offset:5120
	ds_read_b128 v[202:205], v163 offset:6144
	ds_read_b128 v[206:209], v163 offset:7168
	global_load_lds_dwordx4 v[210:211], off
	v_lshl_add_u64 v[210:211], s[28:29], 0, v[150:151]
	s_add_i32 m0, s41, 0xe000
	s_nop 0
	global_load_lds_dwordx4 v[210:211], off
	s_waitcnt vmcnt(8)
	s_waitcnt lgkmcnt(0)
	s_barrier
	v_mfma_f32_16x16x32_bf16 v[140:143], v[64:67], v[178:181], v[140:143]
	v_mfma_f32_16x16x32_bf16 v[136:139], v[112:115], v[178:181], v[136:139]
	v_mfma_f32_16x16x32_bf16 v[124:127], v[64:67], v[186:189], v[124:127]
	v_mfma_f32_16x16x32_bf16 v[116:119], v[112:115], v[186:189], v[116:119]
	v_mfma_f32_16x16x32_bf16 v[96:99], v[64:67], v[194:197], v[96:99]
	v_mfma_f32_16x16x32_bf16 v[92:95], v[112:115], v[194:197], v[92:95]
	v_mfma_f32_16x16x32_bf16 v[80:83], v[64:67], v[202:205], v[80:83]
	v_mfma_f32_16x16x32_bf16 v[76:79], v[112:115], v[202:205], v[76:79]
	v_mfma_f32_16x16x32_bf16 v[140:143], v[108:111], v[182:185], v[140:143]
	v_mfma_f32_16x16x32_bf16 v[136:139], v[120:123], v[182:185], v[136:139]
	v_mfma_f32_16x16x32_bf16 v[124:127], v[108:111], v[190:193], v[124:127]
	v_mfma_f32_16x16x32_bf16 v[116:119], v[120:123], v[190:193], v[116:119]
	v_mfma_f32_16x16x32_bf16 v[96:99], v[108:111], v[198:201], v[96:99]
	v_mfma_f32_16x16x32_bf16 v[92:95], v[120:123], v[198:201], v[92:95]
	v_mfma_f32_16x16x32_bf16 v[80:83], v[108:111], v[206:209], v[80:83]
	v_mfma_f32_16x16x32_bf16 v[76:79], v[120:123], v[206:209], v[76:79]
	v_mfma_f32_16x16x32_bf16 v[132:135], v[154:157], v[178:181], v[132:135]
	v_mfma_f32_16x16x32_bf16 v[128:131], v[168:171], v[178:181], v[128:131]
	v_mfma_f32_16x16x32_bf16 v[104:107], v[154:157], v[186:189], v[104:107]
	v_mfma_f32_16x16x32_bf16 v[100:103], v[168:171], v[186:189], v[100:103]
	v_mfma_f32_16x16x32_bf16 v[88:91], v[154:157], v[194:197], v[88:91]
	v_mfma_f32_16x16x32_bf16 v[84:87], v[168:171], v[194:197], v[84:87]
	v_mfma_f32_16x16x32_bf16 v[72:75], v[154:157], v[202:205], v[72:75]
	v_mfma_f32_16x16x32_bf16 v[68:71], v[168:171], v[202:205], v[68:71]
	v_mfma_f32_16x16x32_bf16 v[132:135], v[164:167], v[182:185], v[132:135]
	v_mfma_f32_16x16x32_bf16 v[128:131], v[172:175], v[182:185], v[128:131]
	v_mfma_f32_16x16x32_bf16 v[104:107], v[164:167], v[190:193], v[104:107]
	v_mfma_f32_16x16x32_bf16 v[100:103], v[172:175], v[190:193], v[100:103]
	v_mfma_f32_16x16x32_bf16 v[88:91], v[164:167], v[198:201], v[88:91]
	v_mfma_f32_16x16x32_bf16 v[84:87], v[172:175], v[198:201], v[84:87]
	v_mfma_f32_16x16x32_bf16 v[72:75], v[164:167], v[206:209], v[72:75]
	v_mfma_f32_16x16x32_bf16 v[68:71], v[172:175], v[206:209], v[68:71]
	s_barrier
	s_add_i32 s20, s60, s3
	v_lshl_add_u64 v[210:211], s[36:37], 0, v[146:147]
	s_mov_b32 m0, s20
	ds_read_b128 v[178:181], v163 offset:16384
	ds_read_b128 v[182:185], v163 offset:17408
	ds_read_b128 v[186:189], v163 offset:18432
	ds_read_b128 v[190:193], v163 offset:19456
	ds_read_b128 v[194:197], v163 offset:20480
	ds_read_b128 v[198:201], v163 offset:21504
	ds_read_b128 v[202:205], v163 offset:22528
	ds_read_b128 v[206:209], v163 offset:23552
	global_load_lds_dwordx4 v[210:211], off
	s_add_i32 m0, s20, 0x2000
	s_add_u32 s20, s36, 0xb0000
	v_lshl_add_u64 v[212:213], s[36:37], 0, v[144:145]
	s_addc_u32 s21, s37, 0
	s_add_i32 s28, s61, s3
	global_load_lds_dwordx4 v[212:213], off
	v_lshl_add_u64 v[214:215], s[20:21], 0, v[146:147]
	s_mov_b32 m0, s28
	v_lshl_add_u64 v[216:217], s[38:39], 0, v[144:145]
	global_load_lds_dwordx4 v[214:215], off
	v_lshl_add_u64 v[214:215], s[20:21], 0, v[144:145]
	s_add_i32 m0, s28, 0x2000
	s_nop 0
	global_load_lds_dwordx4 v[214:215], off
	v_lshl_add_u64 v[214:215], s[38:39], 0, v[146:147]
	s_mov_b32 m0, s41
	s_nop 0
	global_load_lds_dwordx4 v[214:215], off
	s_mov_b32 m0, s42
	s_nop 0
	global_load_lds_dwordx4 v[216:217], off
	s_waitcnt vmcnt(8)
	s_waitcnt lgkmcnt(0)
	s_barrier
; #define PG8_STAGE(bufoff, gbase, voff) do { _Pragma("unroll") for (int _i = 0; _i < 2; ++_i) \
;         __builtin_amdgcn_global_load_lds((const unsigned*)((const char*)(gbase) + (voff)[_i]), (PG8_LAS unsigned*)(lds + (bufoff) + ldsw + _i * 8192), 16, 0, 0); } while (0)
; #define PG8_LDA(dst, b, h) do { _Pragma("unroll") for (int m = 0; m < 4; ++m) _Pragma("unroll") for (int k = 0; k < 2; ++k) dst[m][k] = *(const PG8_LAS bf16x8*)(lds + PG8_SA(b, h) + aoff + m * 2048 + k * 1024); } while (0)
; #define PG8_LDB(dst, b, h) do { _Pragma("unroll") for (int n = 0; n < 2; ++n) _Pragma("unroll") for (int k = 0; k < 2; ++k) dst[n][k] = *(const PG8_LAS bf16x8*)(lds + PG8_SB(b, h) + boff + n * 2048 + k * 1024); } while (0)
; #define PG8_MMA(ai, bj, At, Bt) do { __builtin_amdgcn_s_setprio(1); _Pragma("unroll") for (int m = 0; m < 4; ++m) _Pragma("unroll") for (int n = 0; n < 2; ++n) _Pragma("unroll") for (int k = 0; k < 2; ++k) \
;         acc[ai][bj][m][n] = __builtin_amdgcn_mfma_f32_16x16x32_bf16(Bt[n][k], At[m][k], acc[ai][bj][m][n], 0, 0, 0); __builtin_amdgcn_s_setprio(0); } while (0)
; #define PG8_WAIT_V(n) asm volatile("s_waitcnt vmcnt(" #n ")" ::: "memory")
; #define PG8_WAIT_L(n) asm volatile("s_waitcnt lgkmcnt(" #n ")" ::: "memory")
; #define PG8_BAR __builtin_amdgcn_s_barrier()
; #define PG8_SCHED __builtin_amdgcn_sched_barrier(0)
; template <class Epi, class Sched, bool ALIGN_EPI = false, bool SP2 = false>
; __device__ __forceinline__ void gemm_phase(PG8_LAS unsigned char* lds, const Gemm g, const Sched& S, const Epi& E) {
;     ...
;             PG8_WAIT_V(8); PG8_WAIT_L(0); PG8_BAR; PG8_MMA(0, 0, At, B0); PG8_MMA(0, 1, At, B1); PG8_BAR; PG8_SCHED;
;             PG8_LDA(At, 0, 1); PG8_STAGE(PG8_SB(0, 0), b2, voffB); PG8_STAGE(PG8_SB(0, 1), b2 + hstep, voffB); PG8_STAGE(PG8_SA(0, 0), a2, voffA);
;             PG8_WAIT_V(8); PG8_WAIT_L(0); PG8_BAR; PG8_MMA(1, 0, At, B0); PG8_MMA(1, 1, At, B1); PG8_BAR; PG8_SCHED;
;             PG8_LDB(B0, 1, 0); PG8_LDB(B1, 1, 1); PG8_SCHED; PG8_LDA(At, 1, 0); PG8_STAGE(PG8_SA(0, 1), a2 + hstep, voffA);
;             PG8_WAIT_V(8); PG8_WAIT_L(0); PG8_BAR; PG8_MMA(0, 0, At, B0); PG8_MMA(0, 1, At, B1); PG8_BAR; PG8_SCHED;
	v_mfma_f32_16x16x32_bf16 v[60:63], v[64:67], v[178:181], v[60:63]
	v_mfma_f32_16x16x32_bf16 v[56:59], v[112:115], v[178:181], v[56:59]
	v_mfma_f32_16x16x32_bf16 v[44:47], v[64:67], v[186:189], v[44:47]
	v_mfma_f32_16x16x32_bf16 v[40:43], v[112:115], v[186:189], v[40:43]
	v_mfma_f32_16x16x32_bf16 v[28:31], v[64:67], v[194:197], v[28:31]
	v_mfma_f32_16x16x32_bf16 v[24:27], v[112:115], v[194:197], v[24:27]
	v_mfma_f32_16x16x32_bf16 v[16:19], v[64:67], v[202:205], v[16:19]
	v_mfma_f32_16x16x32_bf16 v[8:11], v[112:115], v[202:205], v[8:11]
	v_mfma_f32_16x16x32_bf16 v[60:63], v[108:111], v[182:185], v[60:63]
	v_mfma_f32_16x16x32_bf16 v[56:59], v[120:123], v[182:185], v[56:59]
	v_mfma_f32_16x16x32_bf16 v[44:47], v[108:111], v[190:193], v[44:47]
	v_mfma_f32_16x16x32_bf16 v[40:43], v[120:123], v[190:193], v[40:43]
	v_mfma_f32_16x16x32_bf16 v[28:31], v[108:111], v[198:201], v[28:31]
	v_mfma_f32_16x16x32_bf16 v[24:27], v[120:123], v[198:201], v[24:27]
	v_mfma_f32_16x16x32_bf16 v[16:19], v[108:111], v[206:209], v[16:19]
	v_mfma_f32_16x16x32_bf16 v[8:11], v[120:123], v[206:209], v[8:11]
	v_mfma_f32_16x16x32_bf16 v[52:55], v[154:157], v[178:181], v[52:55]
	v_mfma_f32_16x16x32_bf16 v[48:51], v[168:171], v[178:181], v[48:51]
	v_mfma_f32_16x16x32_bf16 v[36:39], v[154:157], v[186:189], v[36:39]
	v_mfma_f32_16x16x32_bf16 v[32:35], v[168:171], v[186:189], v[32:35]
	v_mfma_f32_16x16x32_bf16 v[20:23], v[154:157], v[194:197], v[20:23]
	v_mfma_f32_16x16x32_bf16 v[12:15], v[168:171], v[194:197], v[12:15]
	v_mfma_f32_16x16x32_bf16 v[4:7], v[154:157], v[202:205], v[4:7]
	v_mfma_f32_16x16x32_bf16 v[0:3], v[168:171], v[202:205], v[0:3]
	v_mfma_f32_16x16x32_bf16 v[52:55], v[164:167], v[182:185], v[52:55]
	v_mfma_f32_16x16x32_bf16 v[48:51], v[172:175], v[182:185], v[48:51]
	v_mfma_f32_16x16x32_bf16 v[36:39], v[164:167], v[190:193], v[36:39]
	v_mfma_f32_16x16x32_bf16 v[32:35], v[172:175], v[190:193], v[32:35]
	v_mfma_f32_16x16x32_bf16 v[20:23], v[164:167], v[198:201], v[20:23]
	v_mfma_f32_16x16x32_bf16 v[12:15], v[172:175], v[198:201], v[12:15]
	v_mfma_f32_16x16x32_bf16 v[4:7], v[164:167], v[206:209], v[4:7]
	v_mfma_f32_16x16x32_bf16 v[0:3], v[172:175], v[206:209], v[0:3]
	s_barrier
	s_add_i32 s28, 0, 0x18000
	s_add_i32 s29, 0, 0x1c000
	v_add_u32_e32 v120, s28, v159
	v_add_u32_e32 v172, s29, v159
	ds_read_b128 v[64:67], v120
	ds_read_b128 v[108:111], v120 offset:1024
	ds_read_b128 v[112:115], v120 offset:2048
	ds_read_b128 v[120:123], v120 offset:3072
	ds_read_b128 v[154:157], v172
	ds_read_b128 v[164:167], v172 offset:1024
	ds_read_b128 v[168:171], v172 offset:2048
	ds_read_b128 v[172:175], v172 offset:3072
	s_add_u32 s20, s38, 0xb0000
	s_addc_u32 s21, s39, 0
	s_mov_b32 m0, s43
	v_lshl_add_u64 v[218:219], s[20:21], 0, v[146:147]
	ds_read_b128 v[178:181], v163 offset:32768
	ds_read_b128 v[182:185], v163 offset:33792
	ds_read_b128 v[186:189], v163 offset:34816
	ds_read_b128 v[190:193], v163 offset:35840
	ds_read_b128 v[194:197], v163 offset:36864
	ds_read_b128 v[198:201], v163 offset:37888
	ds_read_b128 v[202:205], v163 offset:38912
	ds_read_b128 v[206:209], v163 offset:39936
	global_load_lds_dwordx4 v[218:219], off
	v_lshl_add_u64 v[218:219], s[20:21], 0, v[144:145]
	s_mov_b32 m0, s44
	s_nop 0
	global_load_lds_dwordx4 v[218:219], off
	s_waitcnt vmcnt(8)
	s_waitcnt lgkmcnt(0)
	s_barrier
	v_mfma_f32_16x16x32_bf16 v[140:143], v[64:67], v[178:181], v[140:143]
	v_mfma_f32_16x16x32_bf16 v[136:139], v[112:115], v[178:181], v[136:139]
	v_mfma_f32_16x16x32_bf16 v[124:127], v[64:67], v[186:189], v[124:127]
	v_mfma_f32_16x16x32_bf16 v[116:119], v[112:115], v[186:189], v[116:119]
	v_mfma_f32_16x16x32_bf16 v[96:99], v[64:67], v[194:197], v[96:99]
	v_mfma_f32_16x16x32_bf16 v[92:95], v[112:115], v[194:197], v[92:95]
	v_mfma_f32_16x16x32_bf16 v[80:83], v[64:67], v[202:205], v[80:83]
	v_mfma_f32_16x16x32_bf16 v[76:79], v[112:115], v[202:205], v[76:79]
	v_mfma_f32_16x16x32_bf16 v[140:143], v[108:111], v[182:185], v[140:143]
	v_mfma_f32_16x16x32_bf16 v[136:139], v[120:123], v[182:185], v[136:139]
	v_mfma_f32_16x16x32_bf16 v[124:127], v[108:111], v[190:193], v[124:127]
	v_mfma_f32_16x16x32_bf16 v[116:119], v[120:123], v[190:193], v[116:119]
	v_mfma_f32_16x16x32_bf16 v[96:99], v[108:111], v[198:201], v[96:99]
	v_mfma_f32_16x16x32_bf16 v[92:95], v[120:123], v[198:201], v[92:95]
	v_mfma_f32_16x16x32_bf16 v[80:83], v[108:111], v[206:209], v[80:83]
	v_mfma_f32_16x16x32_bf16 v[76:79], v[120:123], v[206:209], v[76:79]
	v_mfma_f32_16x16x32_bf16 v[132:135], v[154:157], v[178:181], v[132:135]
	v_mfma_f32_16x16x32_bf16 v[128:131], v[168:171], v[178:181], v[128:131]
	v_mfma_f32_16x16x32_bf16 v[104:107], v[154:157], v[186:189], v[104:107]
	v_mfma_f32_16x16x32_bf16 v[100:103], v[168:171], v[186:189], v[100:103]
	v_mfma_f32_16x16x32_bf16 v[88:91], v[154:157], v[194:197], v[88:91]
	v_mfma_f32_16x16x32_bf16 v[84:87], v[168:171], v[194:197], v[84:87]
	v_mfma_f32_16x16x32_bf16 v[72:75], v[154:157], v[202:205], v[72:75]
	v_mfma_f32_16x16x32_bf16 v[68:71], v[168:171], v[202:205], v[68:71]
	v_mfma_f32_16x16x32_bf16 v[132:135], v[164:167], v[182:185], v[132:135]
	v_mfma_f32_16x16x32_bf16 v[128:131], v[172:175], v[182:185], v[128:131]
	v_mfma_f32_16x16x32_bf16 v[104:107], v[164:167], v[190:193], v[104:107]
	v_mfma_f32_16x16x32_bf16 v[100:103], v[172:175], v[190:193], v[100:103]
	v_mfma_f32_16x16x32_bf16 v[88:91], v[164:167], v[198:201], v[88:91]
	v_mfma_f32_16x16x32_bf16 v[84:87], v[172:175], v[198:201], v[84:87]
	v_mfma_f32_16x16x32_bf16 v[72:75], v[164:167], v[206:209], v[72:75]
	v_mfma_f32_16x16x32_bf16 v[68:71], v[172:175], v[206:209], v[68:71]
	s_barrier
; #define PG8_STAGE(bufoff, gbase, voff) do { _Pragma("unroll") for (int _i = 0; _i < 2; ++_i) \
;         __builtin_amdgcn_global_load_lds((const unsigned*)((const char*)(gbase) + (voff)[_i]), (PG8_LAS unsigned*)(lds + (bufoff) + ldsw + _i * 8192), 16, 0, 0); } while (0)
; #define PG8_LDA(dst, b, h) do { _Pragma("unroll") for (int m = 0; m < 4; ++m) _Pragma("unroll") for (int k = 0; k < 2; ++k) dst[m][k] = *(const PG8_LAS bf16x8*)(lds + PG8_SA(b, h) + aoff + m * 2048 + k * 1024); } while (0)
; #define PG8_MMA(ai, bj, At, Bt) do { __builtin_amdgcn_s_setprio(1); _Pragma("unroll") for (int m = 0; m < 4; ++m) _Pragma("unroll") for (int n = 0; n < 2; ++n) _Pragma("unroll") for (int k = 0; k < 2; ++k) \
;         acc[ai][bj][m][n] = __builtin_amdgcn_mfma_f32_16x16x32_bf16(Bt[n][k], At[m][k], acc[ai][bj][m][n], 0, 0, 0); __builtin_amdgcn_s_setprio(0); } while (0)
; #define PG8_WAIT_V(n) asm volatile("s_waitcnt vmcnt(" #n ")" ::: "memory")
; #define PG8_WAIT_L(n) asm volatile("s_waitcnt lgkmcnt(" #n ")" ::: "memory")
; #define PG8_BAR __builtin_amdgcn_s_barrier()
; #define PG8_SCHED __builtin_amdgcn_sched_barrier(0)
; template <class Epi, class Sched, bool ALIGN_EPI = false, bool SP2 = false>
; __device__ __forceinline__ void gemm_phase(PG8_LAS unsigned char* lds, const Gemm g, const Sched& S, const Epi& E) {
;     ...
;         for (int t = 0; t < nt_u; t += 2) {
;             const bool last = (t == nt_u - 2);
;     ...
;             PG8_WAIT_V(8); PG8_WAIT_L(0); PG8_BAR; PG8_MMA(0, 0, At, B0); PG8_MMA(0, 1, At, B1); PG8_BAR; PG8_SCHED;
;             PG8_LDA(At, 1, 1); PG8_STAGE(PG8_SB(1, 0), b3, voffB); PG8_STAGE(PG8_SB(1, 1), b3 + hstep, voffB); PG8_STAGE(PG8_SA(1, 0), a3, voffA);
;             PG8_WAIT_V(8); PG8_WAIT_L(0); PG8_BAR; PG8_MMA(1, 0, At, B0); PG8_MMA(1, 1, At, B1); PG8_BAR; PG8_SCHED;
	s_add_i32 s20, s28, s3
	v_lshl_add_u64 v[210:211], v[210:211], 0, s[8:9]
	s_mov_b32 m0, s20
	ds_read_b128 v[178:181], v163 offset:49152
	ds_read_b128 v[182:185], v163 offset:50176
	ds_read_b128 v[186:189], v163 offset:51200
	ds_read_b128 v[190:193], v163 offset:52224
	ds_read_b128 v[194:197], v163 offset:53248
	ds_read_b128 v[198:201], v163 offset:54272
	ds_read_b128 v[202:205], v163 offset:55296
	ds_read_b128 v[206:209], v163 offset:56320
	global_load_lds_dwordx4 v[210:211], off
	s_add_i32 m0, s20, 0x2000
	s_add_u32 s20, s36, 0xb0080
	v_lshl_add_u64 v[210:211], v[212:213], 0, s[8:9]
	s_addc_u32 s21, s37, 0
	s_add_i32 s28, s29, s3
	global_load_lds_dwordx4 v[210:211], off
	v_lshl_add_u64 v[210:211], s[20:21], 0, v[146:147]
	s_mov_b32 m0, s28
	s_nop 0
	global_load_lds_dwordx4 v[210:211], off
	v_lshl_add_u64 v[210:211], s[20:21], 0, v[144:145]
	s_add_i32 m0, s28, 0x2000
	s_nop 0
	global_load_lds_dwordx4 v[210:211], off
	v_lshl_add_u64 v[210:211], v[214:215], 0, s[8:9]
	s_mov_b32 m0, s46
	s_nop 0
	global_load_lds_dwordx4 v[210:211], off
	v_lshl_add_u64 v[210:211], v[216:217], 0, s[8:9]
	s_mov_b32 m0, s47
	s_nop 0
	global_load_lds_dwordx4 v[210:211], off
	s_waitcnt vmcnt(8)
	s_waitcnt lgkmcnt(0)
	s_barrier
	v_mfma_f32_16x16x32_bf16 v[60:63], v[64:67], v[178:181], v[60:63]
	v_mfma_f32_16x16x32_bf16 v[56:59], v[112:115], v[178:181], v[56:59]
	v_mfma_f32_16x16x32_bf16 v[44:47], v[64:67], v[186:189], v[44:47]
	v_mfma_f32_16x16x32_bf16 v[40:43], v[112:115], v[186:189], v[40:43]
	v_mfma_f32_16x16x32_bf16 v[28:31], v[64:67], v[194:197], v[28:31]
	v_mfma_f32_16x16x32_bf16 v[24:27], v[112:115], v[194:197], v[24:27]
	v_mfma_f32_16x16x32_bf16 v[16:19], v[64:67], v[202:205], v[16:19]
	v_mfma_f32_16x16x32_bf16 v[8:11], v[112:115], v[202:205], v[8:11]
	v_mfma_f32_16x16x32_bf16 v[60:63], v[108:111], v[182:185], v[60:63]
	v_mfma_f32_16x16x32_bf16 v[56:59], v[120:123], v[182:185], v[56:59]
	v_mfma_f32_16x16x32_bf16 v[44:47], v[108:111], v[190:193], v[44:47]
	v_mfma_f32_16x16x32_bf16 v[40:43], v[120:123], v[190:193], v[40:43]
	v_mfma_f32_16x16x32_bf16 v[28:31], v[108:111], v[198:201], v[28:31]
	v_mfma_f32_16x16x32_bf16 v[24:27], v[120:123], v[198:201], v[24:27]
	v_mfma_f32_16x16x32_bf16 v[16:19], v[108:111], v[206:209], v[16:19]
	v_mfma_f32_16x16x32_bf16 v[8:11], v[120:123], v[206:209], v[8:11]
	v_mfma_f32_16x16x32_bf16 v[52:55], v[154:157], v[178:181], v[52:55]
	v_mfma_f32_16x16x32_bf16 v[48:51], v[168:171], v[178:181], v[48:51]
	v_mfma_f32_16x16x32_bf16 v[36:39], v[154:157], v[186:189], v[36:39]
	v_mfma_f32_16x16x32_bf16 v[32:35], v[168:171], v[186:189], v[32:35]
	v_mfma_f32_16x16x32_bf16 v[20:23], v[154:157], v[194:197], v[20:23]
	v_mfma_f32_16x16x32_bf16 v[12:15], v[168:171], v[194:197], v[12:15]
	v_mfma_f32_16x16x32_bf16 v[4:7], v[154:157], v[202:205], v[4:7]
	v_mfma_f32_16x16x32_bf16 v[0:3], v[168:171], v[202:205], v[0:3]
	v_mfma_f32_16x16x32_bf16 v[52:55], v[164:167], v[182:185], v[52:55]
	v_mfma_f32_16x16x32_bf16 v[48:51], v[172:175], v[182:185], v[48:51]
	v_mfma_f32_16x16x32_bf16 v[36:39], v[164:167], v[190:193], v[36:39]
	v_mfma_f32_16x16x32_bf16 v[32:35], v[172:175], v[190:193], v[32:35]
	v_mfma_f32_16x16x32_bf16 v[20:23], v[164:167], v[198:201], v[20:23]
	v_mfma_f32_16x16x32_bf16 v[12:15], v[172:175], v[198:201], v[12:15]
	v_mfma_f32_16x16x32_bf16 v[4:7], v[164:167], v[206:209], v[4:7]
	v_mfma_f32_16x16x32_bf16 v[0:3], v[172:175], v[206:209], v[0:3]
	s_barrier
	s_add_u32 s13, s13, 0x100
	s_addc_u32 s23, s23, 0
	s_cmp_ge_i32 s69, s67
	s_mov_b64 s[28:29], s[30:31]
	s_mov_b32 s36, s69
	s_cbranch_scc0 .LBB0_822
	s_and_b64 vcc, exec, s[10:11]
	s_cbranch_vccz .LBB0_825
	s_barrier
